# hand-written RWKV-7 prompt chain: f32 LDS records, scalar FMA chain, 3 LDS buffers
# speedup vs baseline: 1.0177x; 1.0177x over previous
; DEVI void rw_chain_task(const Params& p, int l, int seq, int head, int quarter, char* smem) {
;     ...
;   const int i = quarter * 16 + wave * 4 + (lane >> 4);
;   const int T = seq < 2 ? SEQ : 32;
;   const int nch = T >> 4;
;   const size_t gbase = seq < 2 ? (size_t)seq * SEQ : (size_t)NP + (seq - 2) * 32;
;   const u16* zC = (const u16*)(p.ws + W_ZC);
;   const u16* KK = (const u16*)(p.ws + W_KK);
;   const u16* BB = (const u16*)(p.ws + W_BB);
;   const float* WW = (const float*)(p.ws + W_WW);
;   u16* cat = (u16*)(p.ws + W_XN);
;   float S[4];
;   if (seq < 2) { S[0] = S[1] = S[2] = S[3] = 0.f; }
;   else {
;     float4 s0 = *(const float4*)(p.in[6] + ((((size_t)l * 8 + (seq - 2)) * 12 + head) * 64 + i) * 64 + jl * 4);
;     S[0] = s0.x; S[1] = s0.y; S[2] = s0.z; S[3] = s0.w;
;   }
;   typedef const __attribute__((address_space(1))) char* gptr_t;
;   typedef const __attribute__((address_space(1))) u32x4* gv4_t;
;   gptr_t lsrc0;
;   int lstride0, ldstA0, ldB;
;   {
;     const int step = tid >> 6;
;     int q = tid & 63;
;     if (q >= 56) q -= 8;
;     const size_t g = gbase + step;
;     if (q < 32) {
;       const int arr = q >> 3, qq = q & 7;
;       int off;
;       if (arr == 0) { lsrc0 = (gptr_t)(zC + g * LZC + head * 64 + qq * 8); lstride0 = LZC * 2; off = 24; }
;       else if (arr == 1) { lsrc0 = (gptr_t)(zC + g * LZC + 768 + head * 64 + qq * 8); lstride0 = LZC * 2; off = 16; }
;       else if (arr == 2) { lsrc0 = (gptr_t)(KK + g * 768 + head * 64 + qq * 8); lstride0 = 768 * 2; off = 0; }
;       else { lsrc0 = (gptr_t)(BB + g * 768 + head * 64 + qq * 8); lstride0 = 768 * 2; off = 8; }
;       ldstA0 = step * 896 + (2 * qq) * 48 + off;
;       ldB = 48;
;     } else if (q < 48) {
;       lsrc0 = (gptr_t)(WW + g * 768 + head * 64 + (q - 32) * 4); lstride0 = 768 * 4;
;       ldstA0 = step * 896 + (q - 32) * 48 + 32;
;       ldB = 8;
;     } else {
;       lsrc0 = (gptr_t)(zC + g * LZC + 1536 + head * 64 + (q - 48) * 8); lstride0 = LZC * 2;
;       ldstA0 = step * 896 + 768 + (q - 48) * 16;
;       ldB = 8;
;     }
;   }
;   u32x4 R0[4], R1[4], R2[4], R3[4];
.LBB0_975:
	s_waitcnt vmcnt(0) lgkmcnt(0)
	s_barrier
	v_readlane_b32 s38, v251, 1
	v_readlane_b32 s39, v251, 2
	v_readlane_b32 s41, v253, 37
	v_readlane_b32 s42, v253, 4
	v_readlane_b32 s43, v252, 61
	v_and_b32_e32 v3, 15, v1
	v_lshrrev_b32_e32 v5, 6, v1
	v_bfe_u32 v6, v1, 4, 2
	v_lshl_add_u32 v154, v5, 2, v6
	s_lshl_b32 s45, s41, 14
	s_lshl_b32 s46, s42, 7
	s_lshl_b32 s47, s41, 26
	v_add_u32_e32 v154, s43, v154
	v_and_b32_e32 v7, 31, v1
	v_lshrrev_b32_e32 v8, 3, v7
	v_and_b32_e32 v9, 7, v1
	v_lshrrev_b32_e32 v10, 5, v1
	v_lshrrev_b32_e32 v11, 1, v8
	v_and_b32_e32 v12, 1, v8
	v_cmp_ne_u32_e64 s[4:5], 0, v12
	v_cmp_ne_u32_e64 s[6:7], 0, v11
	v_mov_b32_e32 v14, 0x1cfd0000
	v_mov_b32_e32 v15, 0x1cfd0600
	v_mov_b32_e32 v16, 0x318b3000
	v_mov_b32_e32 v17, 0x34913000
	v_cndmask_b32_e64 v14, v14, v15, s[4:5]
	v_cndmask_b32_e64 v16, v16, v17, s[4:5]
	v_cndmask_b32_e64 v14, v14, v16, s[6:7]
	v_mov_b32_e32 v15, 0x1400
	v_mov_b32_e32 v17, 0x600
	v_cndmask_b32_e64 v13, v15, v17, s[6:7]
	v_xor_b32_e32 v18, 3, v8
	v_xor_b32_e32 v19, 2, v8
	v_cndmask_b32_e64 v18, v18, v19, s[6:7]
	v_lshl_add_u32 v14, v9, 4, v14
	v_add_u32_e32 v14, s46, v14
	v_add_u32_e32 v20, s45, v10
	v_mad_u32_u24 v14, v20, v13, v14
	v_mov_b32_e32 v15, 0
	v_lshl_add_u64 v[144:145], v[14:15], 0, s[38:39]
	v_lshlrev_b32_e32 v16, 3, v13
	v_mov_b32_e32 v17, 0
	v_lshl_add_u64 v[146:147], v[144:145], 0, v[16:17]
	v_lshlrev_b32_e32 v152, 4, v13
	v_mov_b32_e32 v153, 0
	v_mul_u32_u24_e32 v164, 0x580, v10
	v_mul_u32_u24_e32 v21, 0xa0, v9
	v_add_u32_e32 v164, v164, v21
	v_lshl_add_u32 v164, v18, 4, v164
	v_lshrrev_b32_e32 v22, 4, v1
	v_add_u32_e32 v20, s45, v22
	v_mov_b32_e32 v14, 0x37973000
	v_lshl_add_u32 v14, v3, 4, v14
	v_lshl_add_u32 v14, s42, 8, v14
	v_mov_b32_e32 v13, 0xc00
	v_mad_u32_u24 v14, v20, v13, v14
	v_lshl_add_u64 v[148:149], v[14:15], 0, s[38:39]
	v_mul_u32_u24_e32 v167, 0x580, v22
	v_mul_u32_u24_e32 v21, 0x50, v3
	v_add3_u32 v167, v167, v21, 64
	v_bfe_u32 v23, v1, 1, 3
	v_mov_b32_e32 v14, 0x1cfd0c00
	v_lshl_add_u32 v14, v23, 4, v14
	v_add_u32_e32 v14, s46, v14
	v_mov_b32_e32 v13, 0x1400
	v_mad_u32_u24 v14, v20, v13, v14
	v_lshl_add_u64 v[150:151], v[14:15], 0, s[38:39]
	v_mul_u32_u24_e32 v168, 0x580, v22
	v_lshl_add_u32 v168, v23, 4, v168
	v_add_u32_e32 v168, 0x500, v168
	v_mov_b32_e32 v62, 0xc000
	v_mov_b32_e32 v63, 0
	v_mov_b32_e32 v64, 0x14000
	v_mov_b32_e32 v65, 0
	v_mul_u32_u24_e32 v162, 0x50, v3
	v_lshlrev_b32_e32 v163, 1, v154
	v_add_u32_e32 v163, 0x500, v163
	v_lshlrev_b32_e32 v14, 12, v3
	v_lshl_add_u32 v14, v154, 1, v14
	v_add_u32_e32 v14, s47, v14
	v_add_u32_e32 v14, s46, v14
	v_add_u32_e32 v14, 0x2480a00, v14
	v_lshl_add_u64 v[160:161], v[14:15], 0, s[38:39]
	global_load_dwordx4 v[72:75], v[144:145], off
	global_load_dwordx4 v[76:79], v[146:147], off
	global_load_dwordx4 v[80:83], v[148:149], off
	global_load_dwordx4 v[84:87], v[150:151], off
	v_lshl_add_u64 v[144:145], v[144:145], 0, v[152:153]
	v_lshl_add_u64 v[146:147], v[146:147], 0, v[152:153]
	v_lshl_add_u64 v[148:149], v[148:149], 0, v[62:63]
	v_lshl_add_u64 v[150:151], v[150:151], 0, v[64:65]
	global_load_dwordx4 v[88:91], v[144:145], off
	global_load_dwordx4 v[92:95], v[146:147], off
	global_load_dwordx4 v[96:99], v[148:149], off
	global_load_dwordx4 v[100:103], v[150:151], off
	v_lshl_add_u64 v[144:145], v[144:145], 0, v[152:153]
	v_lshl_add_u64 v[146:147], v[146:147], 0, v[152:153]
	v_lshl_add_u64 v[148:149], v[148:149], 0, v[62:63]
	v_lshl_add_u64 v[150:151], v[150:151], 0, v[64:65]
	global_load_dwordx4 v[104:107], v[144:145], off
	global_load_dwordx4 v[108:111], v[146:147], off
	global_load_dwordx4 v[112:115], v[148:149], off
	global_load_dwordx4 v[116:119], v[150:151], off
	v_lshl_add_u64 v[144:145], v[144:145], 0, v[152:153]
	v_lshl_add_u64 v[146:147], v[146:147], 0, v[152:153]
	v_lshl_add_u64 v[148:149], v[148:149], 0, v[62:63]
	v_lshl_add_u64 v[150:151], v[150:151], 0, v[64:65]
	global_load_dwordx4 v[120:123], v[144:145], off
	global_load_dwordx4 v[124:127], v[146:147], off
	global_load_dwordx4 v[128:131], v[148:149], off
	global_load_dwordx4 v[132:135], v[150:151], off
	v_lshl_add_u64 v[144:145], v[144:145], 0, v[152:153]
	v_lshl_add_u64 v[146:147], v[146:147], 0, v[152:153]
	v_lshl_add_u64 v[148:149], v[148:149], 0, v[62:63]
	v_lshl_add_u64 v[150:151], v[150:151], 0, v[64:65]
	v_cmp_eq_u32_e64 s[4:5], 0, v3
	v_cmp_eq_u32_e64 s[6:7], 1, v3
	v_cmp_eq_u32_e64 s[8:9], 2, v3
	v_cmp_eq_u32_e64 s[10:11], 3, v3
	v_cmp_eq_u32_e64 s[12:13], 4, v3
	v_cmp_eq_u32_e64 s[14:15], 5, v3
	v_cmp_eq_u32_e64 s[16:17], 6, v3
	v_cmp_eq_u32_e64 s[18:19], 7, v3
	v_cmp_eq_u32_e64 s[20:21], 8, v3
	v_cmp_eq_u32_e64 s[22:23], 9, v3
	v_cmp_eq_u32_e64 s[24:25], 10, v3
	v_cmp_eq_u32_e64 s[26:27], 11, v3
	v_cmp_eq_u32_e64 s[28:29], 12, v3
	v_cmp_eq_u32_e64 s[30:31], 13, v3
	v_cmp_eq_u32_e64 s[34:35], 14, v3
	v_cmp_eq_u32_e64 s[36:37], 15, v3
	v_mov_b32_e32 v68, 0
	v_mov_b32_e32 v69, 0
	v_mov_b32_e32 v70, 0
	v_mov_b32_e32 v71, 0
	v_mov_b32_e32 v60, 0
	v_mov_b32_e32 v24, 0
	v_mov_b32_e32 v48, 0
	s_mov_b32 s46, 0x10000
	s_mov_b32 s47, 0
	v_mov_b32_e32 v155, v164
	v_mov_b32_e32 v165, v167
	v_mov_b32_e32 v166, v168
	s_waitcnt vmcnt(12)
; DEVI void rw_chain_task(const Params& p, int l, int seq, int head, int quarter, char* smem) {
;     ...
;   RW_LOAD(R0, 0);
;   RW_LOAD(R1, 1);
;   RW_LOAD(R2, 2);
;   RW_LOAD(R3, 3);
;   RW_STORE(R0, B0);
;   RW_LOAD(R0, 4);
;   if (seq < 2) {
;     for (int c = 0; c < nch; c += 4) {
;       lds_barrier();
;       RW_STORE(R1, B1);
;       RW_LOAD(R1, c + 5);
;       RW_COMPUTE(B0, c);
	v_lshlrev_b32_e32 v136, 16, v72
	v_and_b32_e32 v137, 0xffff0000, v72
	v_lshlrev_b32_e32 v138, 16, v73
	v_and_b32_e32 v139, 0xffff0000, v73
	v_lshlrev_b32_e32 v140, 16, v74
	v_and_b32_e32 v141, 0xffff0000, v74
	v_lshlrev_b32_e32 v142, 16, v75
	v_and_b32_e32 v143, 0xffff0000, v75
	ds_write_b128 v155, v[136:139] offset:0
	ds_write_b128 v155, v[140:143] offset:80
	v_lshlrev_b32_e32 v136, 16, v76
	v_and_b32_e32 v137, 0xffff0000, v76
	v_lshlrev_b32_e32 v138, 16, v77
	v_and_b32_e32 v139, 0xffff0000, v77
	v_lshlrev_b32_e32 v140, 16, v78
	v_and_b32_e32 v141, 0xffff0000, v78
	v_lshlrev_b32_e32 v142, 16, v79
	v_and_b32_e32 v143, 0xffff0000, v79
	ds_write_b128 v155, v[136:139] offset:11264
	ds_write_b128 v155, v[140:143] offset:11344
	ds_write_b128 v165, v[80:83]
	ds_write_b128 v166, v[84:87]
	global_load_dwordx4 v[72:75], v[144:145], off
	global_load_dwordx4 v[76:79], v[146:147], off
	global_load_dwordx4 v[80:83], v[148:149], off
	global_load_dwordx4 v[84:87], v[150:151], off
	v_lshl_add_u64 v[144:145], v[144:145], 0, v[152:153]
	v_lshl_add_u64 v[146:147], v[146:147], 0, v[152:153]
	v_lshl_add_u64 v[148:149], v[148:149], 0, v[62:63]
	v_lshl_add_u64 v[150:151], v[150:151], 0, v[64:65]
	v_add_u32_e32 v155, 0x5800, v164
	v_add_u32_e32 v165, 0x5800, v167
	v_add_u32_e32 v166, 0x5800, v168
	s_waitcnt vmcnt(12)
	v_lshlrev_b32_e32 v136, 16, v88
	v_and_b32_e32 v137, 0xffff0000, v88
	v_lshlrev_b32_e32 v138, 16, v89
	v_and_b32_e32 v139, 0xffff0000, v89
	v_lshlrev_b32_e32 v140, 16, v90
	v_and_b32_e32 v141, 0xffff0000, v90
	v_lshlrev_b32_e32 v142, 16, v91
	v_and_b32_e32 v143, 0xffff0000, v91
	ds_write_b128 v155, v[136:139] offset:0
	ds_write_b128 v155, v[140:143] offset:80
	v_lshlrev_b32_e32 v136, 16, v92
	v_and_b32_e32 v137, 0xffff0000, v92
	v_lshlrev_b32_e32 v138, 16, v93
	v_and_b32_e32 v139, 0xffff0000, v93
	v_lshlrev_b32_e32 v140, 16, v94
	v_and_b32_e32 v141, 0xffff0000, v94
	v_lshlrev_b32_e32 v142, 16, v95
	v_and_b32_e32 v143, 0xffff0000, v95
	ds_write_b128 v155, v[136:139] offset:11264
	ds_write_b128 v155, v[140:143] offset:11344
	ds_write_b128 v165, v[96:99]
	ds_write_b128 v166, v[100:103]
	global_load_dwordx4 v[88:91], v[144:145], off
	global_load_dwordx4 v[92:95], v[146:147], off
	global_load_dwordx4 v[96:99], v[148:149], off
	global_load_dwordx4 v[100:103], v[150:151], off
	v_lshl_add_u64 v[144:145], v[144:145], 0, v[152:153]
	v_lshl_add_u64 v[146:147], v[146:147], 0, v[152:153]
	v_lshl_add_u64 v[148:149], v[148:149], 0, v[62:63]
	v_lshl_add_u64 v[150:151], v[150:151], 0, v[64:65]
	s_mov_b32 s42, 0xb000
	s_mov_b32 s43, 0
	s_mov_b32 s45, 0x5800
	s_mov_b32 s41, 0
	s_waitcnt lgkmcnt(0)
	s_barrier
	ds_read_b128 v[16:19], v162 offset:48
	ds_read_b128 v[4:7], v162 offset:0
	ds_read_b128 v[8:11], v162 offset:16
	ds_read_b128 v[12:15], v162 offset:32
	ds_read_b128 v[20:23], v162 offset:64
	ds_read_u16_d16_hi v24, v163 offset:0
.Lrwc_loop:
	s_waitcnt lgkmcnt(0)
	s_barrier
	s_mov_b32 vcc_lo, s42
	s_mov_b32 s42, s43
	s_mov_b32 s43, s45
	s_mov_b32 s45, vcc_lo
	v_add_u32_e32 v156, s42, v162
	v_add_u32_e32 v157, s42, v163
	v_add_u32_e32 v155, s45, v164
	v_add_u32_e32 v165, s45, v167
	v_add_u32_e32 v166, s45, v168
	s_waitcnt lgkmcnt(0)
	v_mul_f32_e32 v25, v68, v4
	v_mul_f32_e32 v50, v68, v40
	v_fmac_f32_e32 v25, v69, v5
	v_fmac_f32_e32 v50, v69, v41
	v_fmac_f32_e32 v25, v70, v6
	v_fmac_f32_e32 v50, v70, v42
	v_fmac_f32_e32 v25, v71, v7
	v_fmac_f32_e32 v50, v71, v43
	v_mul_f32_e32 v52, v24, v12
	ds_read_b128 v[40:43], v156 offset:1456
	v_add_f32_dpp v25, v25, v25 row_ror:8 row_mask:0xf bank_mask:0xf bound_ctrl:1
	v_mul_f32_e32 v53, v24, v13
	v_add_f32_dpp v50, v50, v50 row_ror:8 row_mask:0xf bank_mask:0xf bound_ctrl:1
	ds_read_b128 v[28:31], v156 offset:1408
	v_mul_f32_e32 v54, v24, v14
	ds_read_b128 v[32:35], v156 offset:1424
	v_add_f32_dpp v25, v25, v25 row_ror:4 row_mask:0xf bank_mask:0xf bound_ctrl:1
	v_mul_f32_e32 v55, v24, v15
	v_add_f32_dpp v50, v50, v50 row_ror:4 row_mask:0xf bank_mask:0xf bound_ctrl:1
	ds_read_b128 v[36:39], v156 offset:1440
	v_fma_f32 v56, v68, v20, v52
	ds_read_b128 v[44:47], v156 offset:1472
	v_add_f32_dpp v25, v25, v25 row_ror:2 row_mask:0xf bank_mask:0xf bound_ctrl:1
	v_fma_f32 v57, v69, v21, v53
	v_add_f32_dpp v50, v50, v50 row_ror:2 row_mask:0xf bank_mask:0xf bound_ctrl:1
	ds_read_u16_d16_hi v48, v157 offset:1408
	v_fma_f32 v58, v70, v22, v54
	v_add_f32_dpp v25, v25, v25 row_ror:1 row_mask:0xf bank_mask:0xf bound_ctrl:1
	v_fma_f32 v59, v71, v23, v55
	v_add_f32_dpp v50, v50, v50 row_ror:1 row_mask:0xf bank_mask:0xf bound_ctrl:1
	s_nop 0
	v_fma_f32 v68, -v25, v8, v56
	v_fma_f32 v69, -v25, v9, v57
	v_fma_f32 v70, -v25, v10, v58
	v_fma_f32 v71, -v25, v11, v59
	v_cndmask_b32_e64 v60, v60, v50, s[36:37]
	s_cmp_eq_u32 s41, 0
	s_cbranch_scc1 .Lrwc_nostore
	v_bfe_u32 v61, v60, 16, 1
	v_add3_u32 v61, v60, v61, s33
	global_store_short_d16_hi v[160:161], v61, off
	v_lshl_add_u64 v[160:161], v[160:161], 0, s[46:47]
.Lrwc_nostore:
	s_waitcnt lgkmcnt(0)
	v_mul_f32_e32 v49, v68, v28
	v_mul_f32_e32 v26, v68, v16
	v_fmac_f32_e32 v49, v69, v29
	v_fmac_f32_e32 v26, v69, v17
	v_fmac_f32_e32 v49, v70, v30
	v_fmac_f32_e32 v26, v70, v18
	v_fmac_f32_e32 v49, v71, v31
	v_fmac_f32_e32 v26, v71, v19
	v_mul_f32_e32 v52, v48, v36
	ds_read_b128 v[16:19], v156 offset:2864
	v_add_f32_dpp v49, v49, v49 row_ror:8 row_mask:0xf bank_mask:0xf bound_ctrl:1
	v_mul_f32_e32 v53, v48, v37
	v_add_f32_dpp v26, v26, v26 row_ror:8 row_mask:0xf bank_mask:0xf bound_ctrl:1
	ds_read_b128 v[4:7], v156 offset:2816
	v_mul_f32_e32 v54, v48, v38
	ds_read_b128 v[8:11], v156 offset:2832
	v_add_f32_dpp v49, v49, v49 row_ror:4 row_mask:0xf bank_mask:0xf bound_ctrl:1
	v_mul_f32_e32 v55, v48, v39
	v_add_f32_dpp v26, v26, v26 row_ror:4 row_mask:0xf bank_mask:0xf bound_ctrl:1
	ds_read_b128 v[12:15], v156 offset:2848
	v_fma_f32 v56, v68, v44, v52
	ds_read_b128 v[20:23], v156 offset:2880
	v_add_f32_dpp v49, v49, v49 row_ror:2 row_mask:0xf bank_mask:0xf bound_ctrl:1
	v_fma_f32 v57, v69, v45, v53
	v_add_f32_dpp v26, v26, v26 row_ror:2 row_mask:0xf bank_mask:0xf bound_ctrl:1
	ds_read_u16_d16_hi v24, v157 offset:2816
	v_fma_f32 v58, v70, v46, v54
	s_waitcnt vmcnt(12)
	v_add_f32_dpp v49, v49, v49 row_ror:1 row_mask:0xf bank_mask:0xf bound_ctrl:1
	v_fma_f32 v59, v71, v47, v55
	v_add_f32_dpp v26, v26, v26 row_ror:1 row_mask:0xf bank_mask:0xf bound_ctrl:1
	v_lshlrev_b32_e32 v136, 16, v104
	s_nop 0
	v_fma_f32 v68, -v49, v32, v56
	v_fma_f32 v69, -v49, v33, v57
	v_fma_f32 v70, -v49, v34, v58
	v_fma_f32 v71, -v49, v35, v59
	v_cndmask_b32_e64 v60, v60, v26, s[4:5]
	v_and_b32_e32 v137, 0xffff0000, v104
	s_waitcnt lgkmcnt(0)
	v_mul_f32_e32 v25, v68, v4
	v_mul_f32_e32 v50, v68, v40
	v_fmac_f32_e32 v25, v69, v5
	v_fmac_f32_e32 v50, v69, v41
	v_fmac_f32_e32 v25, v70, v6
	v_fmac_f32_e32 v50, v70, v42
	v_fmac_f32_e32 v25, v71, v7
	v_fmac_f32_e32 v50, v71, v43
	v_mul_f32_e32 v52, v24, v12
	ds_read_b128 v[40:43], v156 offset:4272
	v_add_f32_dpp v25, v25, v25 row_ror:8 row_mask:0xf bank_mask:0xf bound_ctrl:1
	v_mul_f32_e32 v53, v24, v13
	v_add_f32_dpp v50, v50, v50 row_ror:8 row_mask:0xf bank_mask:0xf bound_ctrl:1
	ds_read_b128 v[28:31], v156 offset:4224
	v_mul_f32_e32 v54, v24, v14
	ds_read_b128 v[32:35], v156 offset:4240
	v_add_f32_dpp v25, v25, v25 row_ror:4 row_mask:0xf bank_mask:0xf bound_ctrl:1
	v_mul_f32_e32 v55, v24, v15
	v_add_f32_dpp v50, v50, v50 row_ror:4 row_mask:0xf bank_mask:0xf bound_ctrl:1
	ds_read_b128 v[36:39], v156 offset:4256
	v_fma_f32 v56, v68, v20, v52
	ds_read_b128 v[44:47], v156 offset:4288
	v_add_f32_dpp v25, v25, v25 row_ror:2 row_mask:0xf bank_mask:0xf bound_ctrl:1
	v_fma_f32 v57, v69, v21, v53
	v_add_f32_dpp v50, v50, v50 row_ror:2 row_mask:0xf bank_mask:0xf bound_ctrl:1
	ds_read_u16_d16_hi v48, v157 offset:4224
	v_fma_f32 v58, v70, v22, v54
	v_lshlrev_b32_e32 v138, 16, v105
	v_add_f32_dpp v25, v25, v25 row_ror:1 row_mask:0xf bank_mask:0xf bound_ctrl:1
	v_fma_f32 v59, v71, v23, v55
	v_add_f32_dpp v50, v50, v50 row_ror:1 row_mask:0xf bank_mask:0xf bound_ctrl:1
	v_and_b32_e32 v139, 0xffff0000, v105
	s_nop 0
	v_fma_f32 v68, -v25, v8, v56
	v_fma_f32 v69, -v25, v9, v57
	v_fma_f32 v70, -v25, v10, v58
	v_fma_f32 v71, -v25, v11, v59
	v_cndmask_b32_e64 v60, v60, v50, s[6:7]
	v_lshlrev_b32_e32 v140, 16, v106
	s_waitcnt lgkmcnt(0)
	v_mul_f32_e32 v49, v68, v28
	v_mul_f32_e32 v26, v68, v16
	v_fmac_f32_e32 v49, v69, v29
	v_fmac_f32_e32 v26, v69, v17
	v_fmac_f32_e32 v49, v70, v30
	v_fmac_f32_e32 v26, v70, v18
	v_fmac_f32_e32 v49, v71, v31
	v_fmac_f32_e32 v26, v71, v19
	v_mul_f32_e32 v52, v48, v36
	ds_read_b128 v[16:19], v156 offset:5680
	v_add_f32_dpp v49, v49, v49 row_ror:8 row_mask:0xf bank_mask:0xf bound_ctrl:1
	v_mul_f32_e32 v53, v48, v37
	v_add_f32_dpp v26, v26, v26 row_ror:8 row_mask:0xf bank_mask:0xf bound_ctrl:1
	ds_read_b128 v[4:7], v156 offset:5632
	v_mul_f32_e32 v54, v48, v38
	ds_read_b128 v[8:11], v156 offset:5648
	v_add_f32_dpp v49, v49, v49 row_ror:4 row_mask:0xf bank_mask:0xf bound_ctrl:1
	v_mul_f32_e32 v55, v48, v39
	v_add_f32_dpp v26, v26, v26 row_ror:4 row_mask:0xf bank_mask:0xf bound_ctrl:1
	ds_read_b128 v[12:15], v156 offset:5664
	v_fma_f32 v56, v68, v44, v52
	ds_read_b128 v[20:23], v156 offset:5696
	v_add_f32_dpp v49, v49, v49 row_ror:2 row_mask:0xf bank_mask:0xf bound_ctrl:1
	v_fma_f32 v57, v69, v45, v53
	v_add_f32_dpp v26, v26, v26 row_ror:2 row_mask:0xf bank_mask:0xf bound_ctrl:1
	ds_read_u16_d16_hi v24, v157 offset:5632
	v_fma_f32 v58, v70, v46, v54
	v_and_b32_e32 v141, 0xffff0000, v106
	v_add_f32_dpp v49, v49, v49 row_ror:1 row_mask:0xf bank_mask:0xf bound_ctrl:1
	v_fma_f32 v59, v71, v47, v55
	v_add_f32_dpp v26, v26, v26 row_ror:1 row_mask:0xf bank_mask:0xf bound_ctrl:1
	v_lshlrev_b32_e32 v142, 16, v107
	s_nop 0
	v_fma_f32 v68, -v49, v32, v56
	v_fma_f32 v69, -v49, v33, v57
	v_fma_f32 v70, -v49, v34, v58
	v_fma_f32 v71, -v49, v35, v59
	v_cndmask_b32_e64 v60, v60, v26, s[8:9]
	v_and_b32_e32 v143, 0xffff0000, v107
	s_waitcnt lgkmcnt(0)
	v_mul_f32_e32 v25, v68, v4
	v_mul_f32_e32 v50, v68, v40
	v_fmac_f32_e32 v25, v69, v5
	v_fmac_f32_e32 v50, v69, v41
	v_fmac_f32_e32 v25, v70, v6
	v_fmac_f32_e32 v50, v70, v42
	v_fmac_f32_e32 v25, v71, v7
	v_fmac_f32_e32 v50, v71, v43
	v_mul_f32_e32 v52, v24, v12
	ds_read_b128 v[40:43], v156 offset:7088
	v_add_f32_dpp v25, v25, v25 row_ror:8 row_mask:0xf bank_mask:0xf bound_ctrl:1
	v_mul_f32_e32 v53, v24, v13
	v_add_f32_dpp v50, v50, v50 row_ror:8 row_mask:0xf bank_mask:0xf bound_ctrl:1
	ds_read_b128 v[28:31], v156 offset:7040
	v_mul_f32_e32 v54, v24, v14
	ds_read_b128 v[32:35], v156 offset:7056
	v_add_f32_dpp v25, v25, v25 row_ror:4 row_mask:0xf bank_mask:0xf bound_ctrl:1
	v_mul_f32_e32 v55, v24, v15
	v_add_f32_dpp v50, v50, v50 row_ror:4 row_mask:0xf bank_mask:0xf bound_ctrl:1
	ds_read_b128 v[36:39], v156 offset:7072
	v_fma_f32 v56, v68, v20, v52
	ds_read_b128 v[44:47], v156 offset:7104
	v_add_f32_dpp v25, v25, v25 row_ror:2 row_mask:0xf bank_mask:0xf bound_ctrl:1
	v_fma_f32 v57, v69, v21, v53
	v_add_f32_dpp v50, v50, v50 row_ror:2 row_mask:0xf bank_mask:0xf bound_ctrl:1
	ds_read_u16_d16_hi v48, v157 offset:7040
	v_fma_f32 v58, v70, v22, v54
	ds_write_b128 v155, v[136:139] offset:0
	v_add_f32_dpp v25, v25, v25 row_ror:1 row_mask:0xf bank_mask:0xf bound_ctrl:1
	v_fma_f32 v59, v71, v23, v55
	v_add_f32_dpp v50, v50, v50 row_ror:1 row_mask:0xf bank_mask:0xf bound_ctrl:1
	ds_write_b128 v155, v[140:143] offset:80
	s_nop 0
	v_fma_f32 v68, -v25, v8, v56
	v_fma_f32 v69, -v25, v9, v57
	v_fma_f32 v70, -v25, v10, v58
	v_fma_f32 v71, -v25, v11, v59
	v_cndmask_b32_e64 v60, v60, v50, s[10:11]
	v_lshlrev_b32_e32 v136, 16, v108
	s_waitcnt lgkmcnt(0)
	v_mul_f32_e32 v49, v68, v28
	v_mul_f32_e32 v26, v68, v16
	v_fmac_f32_e32 v49, v69, v29
	v_fmac_f32_e32 v26, v69, v17
	v_fmac_f32_e32 v49, v70, v30
	v_fmac_f32_e32 v26, v70, v18
	v_fmac_f32_e32 v49, v71, v31
	v_fmac_f32_e32 v26, v71, v19
	v_mul_f32_e32 v52, v48, v36
	ds_read_b128 v[16:19], v156 offset:8496
	v_add_f32_dpp v49, v49, v49 row_ror:8 row_mask:0xf bank_mask:0xf bound_ctrl:1
	v_mul_f32_e32 v53, v48, v37
	v_add_f32_dpp v26, v26, v26 row_ror:8 row_mask:0xf bank_mask:0xf bound_ctrl:1
	ds_read_b128 v[4:7], v156 offset:8448
	v_mul_f32_e32 v54, v48, v38
	ds_read_b128 v[8:11], v156 offset:8464
	v_add_f32_dpp v49, v49, v49 row_ror:4 row_mask:0xf bank_mask:0xf bound_ctrl:1
	v_mul_f32_e32 v55, v48, v39
	v_add_f32_dpp v26, v26, v26 row_ror:4 row_mask:0xf bank_mask:0xf bound_ctrl:1
	ds_read_b128 v[12:15], v156 offset:8480
	v_fma_f32 v56, v68, v44, v52
	ds_read_b128 v[20:23], v156 offset:8512
	v_add_f32_dpp v49, v49, v49 row_ror:2 row_mask:0xf bank_mask:0xf bound_ctrl:1
	v_fma_f32 v57, v69, v45, v53
	v_add_f32_dpp v26, v26, v26 row_ror:2 row_mask:0xf bank_mask:0xf bound_ctrl:1
	ds_read_u16_d16_hi v24, v157 offset:8448
	v_fma_f32 v58, v70, v46, v54
	v_and_b32_e32 v137, 0xffff0000, v108
	v_add_f32_dpp v49, v49, v49 row_ror:1 row_mask:0xf bank_mask:0xf bound_ctrl:1
	v_fma_f32 v59, v71, v47, v55
	v_add_f32_dpp v26, v26, v26 row_ror:1 row_mask:0xf bank_mask:0xf bound_ctrl:1
	v_lshlrev_b32_e32 v138, 16, v109
	s_nop 0
	v_fma_f32 v68, -v49, v32, v56
	v_fma_f32 v69, -v49, v33, v57
	v_fma_f32 v70, -v49, v34, v58
	v_fma_f32 v71, -v49, v35, v59
	v_cndmask_b32_e64 v60, v60, v26, s[12:13]
	v_and_b32_e32 v139, 0xffff0000, v109
	s_waitcnt lgkmcnt(0)
	v_mul_f32_e32 v25, v68, v4
	v_mul_f32_e32 v50, v68, v40
	v_fmac_f32_e32 v25, v69, v5
	v_fmac_f32_e32 v50, v69, v41
	v_fmac_f32_e32 v25, v70, v6
	v_fmac_f32_e32 v50, v70, v42
	v_fmac_f32_e32 v25, v71, v7
	v_fmac_f32_e32 v50, v71, v43
	v_mul_f32_e32 v52, v24, v12
	ds_read_b128 v[40:43], v156 offset:9904
	v_add_f32_dpp v25, v25, v25 row_ror:8 row_mask:0xf bank_mask:0xf bound_ctrl:1
	v_mul_f32_e32 v53, v24, v13
	v_add_f32_dpp v50, v50, v50 row_ror:8 row_mask:0xf bank_mask:0xf bound_ctrl:1
	ds_read_b128 v[28:31], v156 offset:9856
	v_mul_f32_e32 v54, v24, v14
	ds_read_b128 v[32:35], v156 offset:9872
	v_add_f32_dpp v25, v25, v25 row_ror:4 row_mask:0xf bank_mask:0xf bound_ctrl:1
	v_mul_f32_e32 v55, v24, v15
	v_add_f32_dpp v50, v50, v50 row_ror:4 row_mask:0xf bank_mask:0xf bound_ctrl:1
	ds_read_b128 v[36:39], v156 offset:9888
	v_fma_f32 v56, v68, v20, v52
	ds_read_b128 v[44:47], v156 offset:9920
	v_add_f32_dpp v25, v25, v25 row_ror:2 row_mask:0xf bank_mask:0xf bound_ctrl:1
	v_fma_f32 v57, v69, v21, v53
	v_add_f32_dpp v50, v50, v50 row_ror:2 row_mask:0xf bank_mask:0xf bound_ctrl:1
	ds_read_u16_d16_hi v48, v157 offset:9856
	v_fma_f32 v58, v70, v22, v54
	v_lshlrev_b32_e32 v140, 16, v110
	v_add_f32_dpp v25, v25, v25 row_ror:1 row_mask:0xf bank_mask:0xf bound_ctrl:1
	v_fma_f32 v59, v71, v23, v55
	v_add_f32_dpp v50, v50, v50 row_ror:1 row_mask:0xf bank_mask:0xf bound_ctrl:1
	v_and_b32_e32 v141, 0xffff0000, v110
	s_nop 0
	v_fma_f32 v68, -v25, v8, v56
	v_fma_f32 v69, -v25, v9, v57
	v_fma_f32 v70, -v25, v10, v58
	v_fma_f32 v71, -v25, v11, v59
	v_cndmask_b32_e64 v60, v60, v50, s[14:15]
	v_lshlrev_b32_e32 v142, 16, v111
	s_waitcnt lgkmcnt(0)
	v_mul_f32_e32 v49, v68, v28
	v_mul_f32_e32 v26, v68, v16
	v_fmac_f32_e32 v49, v69, v29
	v_fmac_f32_e32 v26, v69, v17
	v_fmac_f32_e32 v49, v70, v30
	v_fmac_f32_e32 v26, v70, v18
	v_fmac_f32_e32 v49, v71, v31
	v_fmac_f32_e32 v26, v71, v19
	v_mul_f32_e32 v52, v48, v36
	ds_read_b128 v[16:19], v156 offset:11312
	v_add_f32_dpp v49, v49, v49 row_ror:8 row_mask:0xf bank_mask:0xf bound_ctrl:1
	v_mul_f32_e32 v53, v48, v37
	v_add_f32_dpp v26, v26, v26 row_ror:8 row_mask:0xf bank_mask:0xf bound_ctrl:1
	ds_read_b128 v[4:7], v156 offset:11264
	v_mul_f32_e32 v54, v48, v38
	ds_read_b128 v[8:11], v156 offset:11280
	v_add_f32_dpp v49, v49, v49 row_ror:4 row_mask:0xf bank_mask:0xf bound_ctrl:1
	v_mul_f32_e32 v55, v48, v39
	v_add_f32_dpp v26, v26, v26 row_ror:4 row_mask:0xf bank_mask:0xf bound_ctrl:1
	ds_read_b128 v[12:15], v156 offset:11296
	v_fma_f32 v56, v68, v44, v52
	ds_read_b128 v[20:23], v156 offset:11328
	v_add_f32_dpp v49, v49, v49 row_ror:2 row_mask:0xf bank_mask:0xf bound_ctrl:1
	v_fma_f32 v57, v69, v45, v53
	v_add_f32_dpp v26, v26, v26 row_ror:2 row_mask:0xf bank_mask:0xf bound_ctrl:1
	ds_read_u16_d16_hi v24, v157 offset:11264
	v_fma_f32 v58, v70, v46, v54
	v_and_b32_e32 v143, 0xffff0000, v111
	v_add_f32_dpp v49, v49, v49 row_ror:1 row_mask:0xf bank_mask:0xf bound_ctrl:1
	v_fma_f32 v59, v71, v47, v55
	v_add_f32_dpp v26, v26, v26 row_ror:1 row_mask:0xf bank_mask:0xf bound_ctrl:1
	ds_write_b128 v155, v[136:139] offset:11264
	s_nop 0
	v_fma_f32 v68, -v49, v32, v56
	v_fma_f32 v69, -v49, v33, v57
	v_fma_f32 v70, -v49, v34, v58
	v_fma_f32 v71, -v49, v35, v59
	v_cndmask_b32_e64 v60, v60, v26, s[16:17]
	ds_write_b128 v155, v[140:143] offset:11344
	s_waitcnt lgkmcnt(0)
	v_mul_f32_e32 v25, v68, v4
	v_mul_f32_e32 v50, v68, v40
	v_fmac_f32_e32 v25, v69, v5
	v_fmac_f32_e32 v50, v69, v41
	v_fmac_f32_e32 v25, v70, v6
	v_fmac_f32_e32 v50, v70, v42
	v_fmac_f32_e32 v25, v71, v7
	v_fmac_f32_e32 v50, v71, v43
	v_mul_f32_e32 v52, v24, v12
	ds_read_b128 v[40:43], v156 offset:12720
	v_add_f32_dpp v25, v25, v25 row_ror:8 row_mask:0xf bank_mask:0xf bound_ctrl:1
	v_mul_f32_e32 v53, v24, v13
	v_add_f32_dpp v50, v50, v50 row_ror:8 row_mask:0xf bank_mask:0xf bound_ctrl:1
	ds_read_b128 v[28:31], v156 offset:12672
	v_mul_f32_e32 v54, v24, v14
	ds_read_b128 v[32:35], v156 offset:12688
	v_add_f32_dpp v25, v25, v25 row_ror:4 row_mask:0xf bank_mask:0xf bound_ctrl:1
	v_mul_f32_e32 v55, v24, v15
	v_add_f32_dpp v50, v50, v50 row_ror:4 row_mask:0xf bank_mask:0xf bound_ctrl:1
	ds_read_b128 v[36:39], v156 offset:12704
	v_fma_f32 v56, v68, v20, v52
	ds_read_b128 v[44:47], v156 offset:12736
	v_add_f32_dpp v25, v25, v25 row_ror:2 row_mask:0xf bank_mask:0xf bound_ctrl:1
	v_fma_f32 v57, v69, v21, v53
	v_add_f32_dpp v50, v50, v50 row_ror:2 row_mask:0xf bank_mask:0xf bound_ctrl:1
	ds_read_u16_d16_hi v48, v157 offset:12672
	v_fma_f32 v58, v70, v22, v54
	ds_write_b128 v165, v[112:115]
	v_add_f32_dpp v25, v25, v25 row_ror:1 row_mask:0xf bank_mask:0xf bound_ctrl:1
	v_fma_f32 v59, v71, v23, v55
	v_add_f32_dpp v50, v50, v50 row_ror:1 row_mask:0xf bank_mask:0xf bound_ctrl:1
	ds_write_b128 v166, v[116:119]
	s_nop 0
	v_fma_f32 v68, -v25, v8, v56
	v_fma_f32 v69, -v25, v9, v57
	v_fma_f32 v70, -v25, v10, v58
	v_fma_f32 v71, -v25, v11, v59
	v_cndmask_b32_e64 v60, v60, v50, s[18:19]
	global_load_dwordx4 v[104:107], v[144:145], off
	s_waitcnt lgkmcnt(0)
	v_mul_f32_e32 v49, v68, v28
	v_mul_f32_e32 v26, v68, v16
	v_fmac_f32_e32 v49, v69, v29
	v_fmac_f32_e32 v26, v69, v17
	v_fmac_f32_e32 v49, v70, v30
	v_fmac_f32_e32 v26, v70, v18
	v_fmac_f32_e32 v49, v71, v31
	v_fmac_f32_e32 v26, v71, v19
	v_mul_f32_e32 v52, v48, v36
	ds_read_b128 v[16:19], v156 offset:14128
	v_add_f32_dpp v49, v49, v49 row_ror:8 row_mask:0xf bank_mask:0xf bound_ctrl:1
	v_mul_f32_e32 v53, v48, v37
	v_add_f32_dpp v26, v26, v26 row_ror:8 row_mask:0xf bank_mask:0xf bound_ctrl:1
	ds_read_b128 v[4:7], v156 offset:14080
	v_mul_f32_e32 v54, v48, v38
	ds_read_b128 v[8:11], v156 offset:14096
	v_add_f32_dpp v49, v49, v49 row_ror:4 row_mask:0xf bank_mask:0xf bound_ctrl:1
	v_mul_f32_e32 v55, v48, v39
	v_add_f32_dpp v26, v26, v26 row_ror:4 row_mask:0xf bank_mask:0xf bound_ctrl:1
	ds_read_b128 v[12:15], v156 offset:14112
	v_fma_f32 v56, v68, v44, v52
	ds_read_b128 v[20:23], v156 offset:14144
	v_add_f32_dpp v49, v49, v49 row_ror:2 row_mask:0xf bank_mask:0xf bound_ctrl:1
	v_fma_f32 v57, v69, v45, v53
	v_add_f32_dpp v26, v26, v26 row_ror:2 row_mask:0xf bank_mask:0xf bound_ctrl:1
	ds_read_u16_d16_hi v24, v157 offset:14080
	v_fma_f32 v58, v70, v46, v54
	global_load_dwordx4 v[108:111], v[146:147], off
	v_add_f32_dpp v49, v49, v49 row_ror:1 row_mask:0xf bank_mask:0xf bound_ctrl:1
	v_fma_f32 v59, v71, v47, v55
	v_add_f32_dpp v26, v26, v26 row_ror:1 row_mask:0xf bank_mask:0xf bound_ctrl:1
	global_load_dwordx4 v[112:115], v[148:149], off
	s_nop 0
	v_fma_f32 v68, -v49, v32, v56
	v_fma_f32 v69, -v49, v33, v57
	v_fma_f32 v70, -v49, v34, v58
	v_fma_f32 v71, -v49, v35, v59
	v_cndmask_b32_e64 v60, v60, v26, s[20:21]
	global_load_dwordx4 v[116:119], v[150:151], off
	s_waitcnt lgkmcnt(0)
	v_mul_f32_e32 v25, v68, v4
	v_mul_f32_e32 v50, v68, v40
	v_fmac_f32_e32 v25, v69, v5
	v_fmac_f32_e32 v50, v69, v41
	v_fmac_f32_e32 v25, v70, v6
	v_fmac_f32_e32 v50, v70, v42
	v_fmac_f32_e32 v25, v71, v7
	v_fmac_f32_e32 v50, v71, v43
	v_mul_f32_e32 v52, v24, v12
	ds_read_b128 v[40:43], v156 offset:15536
	v_add_f32_dpp v25, v25, v25 row_ror:8 row_mask:0xf bank_mask:0xf bound_ctrl:1
	v_mul_f32_e32 v53, v24, v13
	v_add_f32_dpp v50, v50, v50 row_ror:8 row_mask:0xf bank_mask:0xf bound_ctrl:1
	ds_read_b128 v[28:31], v156 offset:15488
	v_mul_f32_e32 v54, v24, v14
	ds_read_b128 v[32:35], v156 offset:15504
	v_add_f32_dpp v25, v25, v25 row_ror:4 row_mask:0xf bank_mask:0xf bound_ctrl:1
	v_mul_f32_e32 v55, v24, v15
	v_add_f32_dpp v50, v50, v50 row_ror:4 row_mask:0xf bank_mask:0xf bound_ctrl:1
	ds_read_b128 v[36:39], v156 offset:15520
	v_fma_f32 v56, v68, v20, v52
	ds_read_b128 v[44:47], v156 offset:15552
	v_add_f32_dpp v25, v25, v25 row_ror:2 row_mask:0xf bank_mask:0xf bound_ctrl:1
	v_fma_f32 v57, v69, v21, v53
	v_add_f32_dpp v50, v50, v50 row_ror:2 row_mask:0xf bank_mask:0xf bound_ctrl:1
	ds_read_u16_d16_hi v48, v157 offset:15488
	v_fma_f32 v58, v70, v22, v54
	v_lshl_add_u64 v[144:145], v[144:145], 0, v[152:153]
	v_add_f32_dpp v25, v25, v25 row_ror:1 row_mask:0xf bank_mask:0xf bound_ctrl:1
	v_fma_f32 v59, v71, v23, v55
	v_add_f32_dpp v50, v50, v50 row_ror:1 row_mask:0xf bank_mask:0xf bound_ctrl:1
	v_lshl_add_u64 v[146:147], v[146:147], 0, v[152:153]
	s_nop 0
	v_fma_f32 v68, -v25, v8, v56
	v_fma_f32 v69, -v25, v9, v57
	v_fma_f32 v70, -v25, v10, v58
	v_fma_f32 v71, -v25, v11, v59
	v_cndmask_b32_e64 v60, v60, v50, s[22:23]
	v_lshl_add_u64 v[148:149], v[148:149], 0, v[62:63]
	s_waitcnt lgkmcnt(0)
	v_mul_f32_e32 v49, v68, v28
	v_mul_f32_e32 v26, v68, v16
	v_fmac_f32_e32 v49, v69, v29
	v_fmac_f32_e32 v26, v69, v17
	v_fmac_f32_e32 v49, v70, v30
	v_fmac_f32_e32 v26, v70, v18
	v_fmac_f32_e32 v49, v71, v31
	v_fmac_f32_e32 v26, v71, v19
	v_mul_f32_e32 v52, v48, v36
	ds_read_b128 v[16:19], v156 offset:16944
	v_add_f32_dpp v49, v49, v49 row_ror:8 row_mask:0xf bank_mask:0xf bound_ctrl:1
	v_mul_f32_e32 v53, v48, v37
	v_add_f32_dpp v26, v26, v26 row_ror:8 row_mask:0xf bank_mask:0xf bound_ctrl:1
	ds_read_b128 v[4:7], v156 offset:16896
	v_mul_f32_e32 v54, v48, v38
	ds_read_b128 v[8:11], v156 offset:16912
	v_add_f32_dpp v49, v49, v49 row_ror:4 row_mask:0xf bank_mask:0xf bound_ctrl:1
	v_mul_f32_e32 v55, v48, v39
	v_add_f32_dpp v26, v26, v26 row_ror:4 row_mask:0xf bank_mask:0xf bound_ctrl:1
	ds_read_b128 v[12:15], v156 offset:16928
	v_fma_f32 v56, v68, v44, v52
	ds_read_b128 v[20:23], v156 offset:16960
	v_add_f32_dpp v49, v49, v49 row_ror:2 row_mask:0xf bank_mask:0xf bound_ctrl:1
	v_fma_f32 v57, v69, v45, v53
	v_add_f32_dpp v26, v26, v26 row_ror:2 row_mask:0xf bank_mask:0xf bound_ctrl:1
	ds_read_u16_d16_hi v24, v157 offset:16896
	v_fma_f32 v58, v70, v46, v54
	v_lshl_add_u64 v[150:151], v[150:151], 0, v[64:65]
	v_add_f32_dpp v49, v49, v49 row_ror:1 row_mask:0xf bank_mask:0xf bound_ctrl:1
	v_fma_f32 v59, v71, v47, v55
	v_add_f32_dpp v26, v26, v26 row_ror:1 row_mask:0xf bank_mask:0xf bound_ctrl:1
	v_add_u32_e32 v158, s43, v162
	s_nop 0
	v_fma_f32 v68, -v49, v32, v56
	v_fma_f32 v69, -v49, v33, v57
	v_fma_f32 v70, -v49, v34, v58
	v_fma_f32 v71, -v49, v35, v59
	v_cndmask_b32_e64 v60, v60, v26, s[24:25]
	v_add_u32_e32 v159, s43, v163
	s_waitcnt lgkmcnt(0)
	v_mul_f32_e32 v25, v68, v4
	v_mul_f32_e32 v50, v68, v40
	v_fmac_f32_e32 v25, v69, v5
	v_fmac_f32_e32 v50, v69, v41
	v_fmac_f32_e32 v25, v70, v6
	v_fmac_f32_e32 v50, v70, v42
	v_fmac_f32_e32 v25, v71, v7
	v_fmac_f32_e32 v50, v71, v43
	v_mul_f32_e32 v52, v24, v12
	ds_read_b128 v[40:43], v156 offset:18352
	v_add_f32_dpp v25, v25, v25 row_ror:8 row_mask:0xf bank_mask:0xf bound_ctrl:1
	v_mul_f32_e32 v53, v24, v13
	v_add_f32_dpp v50, v50, v50 row_ror:8 row_mask:0xf bank_mask:0xf bound_ctrl:1
	ds_read_b128 v[28:31], v156 offset:18304
	v_mul_f32_e32 v54, v24, v14
	ds_read_b128 v[32:35], v156 offset:18320
	v_add_f32_dpp v25, v25, v25 row_ror:4 row_mask:0xf bank_mask:0xf bound_ctrl:1
	v_mul_f32_e32 v55, v24, v15
	v_add_f32_dpp v50, v50, v50 row_ror:4 row_mask:0xf bank_mask:0xf bound_ctrl:1
	ds_read_b128 v[36:39], v156 offset:18336
	v_fma_f32 v56, v68, v20, v52
	ds_read_b128 v[44:47], v156 offset:18368
	v_add_f32_dpp v25, v25, v25 row_ror:2 row_mask:0xf bank_mask:0xf bound_ctrl:1
	v_fma_f32 v57, v69, v21, v53
	v_add_f32_dpp v50, v50, v50 row_ror:2 row_mask:0xf bank_mask:0xf bound_ctrl:1
	ds_read_u16_d16_hi v48, v157 offset:18304
	v_fma_f32 v58, v70, v22, v54
	v_add_f32_dpp v25, v25, v25 row_ror:1 row_mask:0xf bank_mask:0xf bound_ctrl:1
	v_fma_f32 v59, v71, v23, v55
	v_add_f32_dpp v50, v50, v50 row_ror:1 row_mask:0xf bank_mask:0xf bound_ctrl:1
	s_nop 0
	v_fma_f32 v68, -v25, v8, v56
	v_fma_f32 v69, -v25, v9, v57
	v_fma_f32 v70, -v25, v10, v58
	v_fma_f32 v71, -v25, v11, v59
	v_cndmask_b32_e64 v60, v60, v50, s[26:27]
	s_waitcnt lgkmcnt(0)
; DEVI void rw_chain_task(const Params& p, int l, int seq, int head, int quarter, char* smem) {
;     ...
;     for (int c = 0; c < nch; c += 4) {
;       lds_barrier();
;       RW_STORE(R1, B1);
;       RW_LOAD(R1, c + 5);
;       RW_COMPUTE(B0, c);
;       lds_barrier();
	v_mul_f32_e32 v49, v68, v28
	v_mul_f32_e32 v26, v68, v16
	v_fmac_f32_e32 v49, v69, v29
	v_fmac_f32_e32 v26, v69, v17
	v_fmac_f32_e32 v49, v70, v30
	v_fmac_f32_e32 v26, v70, v18
	v_fmac_f32_e32 v49, v71, v31
	v_fmac_f32_e32 v26, v71, v19
	v_mul_f32_e32 v52, v48, v36
	ds_read_b128 v[16:19], v156 offset:19760
	v_add_f32_dpp v49, v49, v49 row_ror:8 row_mask:0xf bank_mask:0xf bound_ctrl:1
	v_mul_f32_e32 v53, v48, v37
	v_add_f32_dpp v26, v26, v26 row_ror:8 row_mask:0xf bank_mask:0xf bound_ctrl:1
	ds_read_b128 v[4:7], v156 offset:19712
	v_mul_f32_e32 v54, v48, v38
	ds_read_b128 v[8:11], v156 offset:19728
	v_add_f32_dpp v49, v49, v49 row_ror:4 row_mask:0xf bank_mask:0xf bound_ctrl:1
	v_mul_f32_e32 v55, v48, v39
	v_add_f32_dpp v26, v26, v26 row_ror:4 row_mask:0xf bank_mask:0xf bound_ctrl:1
	ds_read_b128 v[12:15], v156 offset:19744
	v_fma_f32 v56, v68, v44, v52
	ds_read_b128 v[20:23], v156 offset:19776
	v_add_f32_dpp v49, v49, v49 row_ror:2 row_mask:0xf bank_mask:0xf bound_ctrl:1
	v_fma_f32 v57, v69, v45, v53
	v_add_f32_dpp v26, v26, v26 row_ror:2 row_mask:0xf bank_mask:0xf bound_ctrl:1
	ds_read_u16_d16_hi v24, v157 offset:19712
	v_fma_f32 v58, v70, v46, v54
	v_add_f32_dpp v49, v49, v49 row_ror:1 row_mask:0xf bank_mask:0xf bound_ctrl:1
	v_fma_f32 v59, v71, v47, v55
	v_add_f32_dpp v26, v26, v26 row_ror:1 row_mask:0xf bank_mask:0xf bound_ctrl:1
	s_nop 0
	v_fma_f32 v68, -v49, v32, v56
	v_fma_f32 v69, -v49, v33, v57
	v_fma_f32 v70, -v49, v34, v58
	v_fma_f32 v71, -v49, v35, v59
	v_cndmask_b32_e64 v60, v60, v26, s[28:29]
	s_waitcnt lgkmcnt(0)
	v_mul_f32_e32 v25, v68, v4
	v_mul_f32_e32 v50, v68, v40
	v_fmac_f32_e32 v25, v69, v5
	v_fmac_f32_e32 v50, v69, v41
	v_fmac_f32_e32 v25, v70, v6
	v_fmac_f32_e32 v50, v70, v42
	v_fmac_f32_e32 v25, v71, v7
	v_fmac_f32_e32 v50, v71, v43
	v_mul_f32_e32 v52, v24, v12
	ds_read_b128 v[40:43], v156 offset:21168
	v_add_f32_dpp v25, v25, v25 row_ror:8 row_mask:0xf bank_mask:0xf bound_ctrl:1
	v_mul_f32_e32 v53, v24, v13
	v_add_f32_dpp v50, v50, v50 row_ror:8 row_mask:0xf bank_mask:0xf bound_ctrl:1
	ds_read_b128 v[28:31], v156 offset:21120
	v_mul_f32_e32 v54, v24, v14
	ds_read_b128 v[32:35], v156 offset:21136
	v_add_f32_dpp v25, v25, v25 row_ror:4 row_mask:0xf bank_mask:0xf bound_ctrl:1
	v_mul_f32_e32 v55, v24, v15
	v_add_f32_dpp v50, v50, v50 row_ror:4 row_mask:0xf bank_mask:0xf bound_ctrl:1
	ds_read_b128 v[36:39], v156 offset:21152
	v_fma_f32 v56, v68, v20, v52
	ds_read_b128 v[44:47], v156 offset:21184
	v_add_f32_dpp v25, v25, v25 row_ror:2 row_mask:0xf bank_mask:0xf bound_ctrl:1
	v_fma_f32 v57, v69, v21, v53
	v_add_f32_dpp v50, v50, v50 row_ror:2 row_mask:0xf bank_mask:0xf bound_ctrl:1
	ds_read_u16_d16_hi v48, v157 offset:21120
	v_fma_f32 v58, v70, v22, v54
	v_add_f32_dpp v25, v25, v25 row_ror:1 row_mask:0xf bank_mask:0xf bound_ctrl:1
	v_fma_f32 v59, v71, v23, v55
	v_add_f32_dpp v50, v50, v50 row_ror:1 row_mask:0xf bank_mask:0xf bound_ctrl:1
	s_nop 0
	v_fma_f32 v68, -v25, v8, v56
	v_fma_f32 v69, -v25, v9, v57
	v_fma_f32 v70, -v25, v10, v58
	v_fma_f32 v71, -v25, v11, v59
	v_cndmask_b32_e64 v60, v60, v50, s[30:31]
	s_waitcnt lgkmcnt(0)
	v_mul_f32_e32 v49, v68, v28
	v_mul_f32_e32 v26, v68, v16
	v_fmac_f32_e32 v49, v69, v29
	v_fmac_f32_e32 v26, v69, v17
	v_fmac_f32_e32 v49, v70, v30
	v_fmac_f32_e32 v26, v70, v18
	v_fmac_f32_e32 v49, v71, v31
	v_fmac_f32_e32 v26, v71, v19
	v_mul_f32_e32 v52, v48, v36
	ds_read_b128 v[16:19], v158 offset:48
	v_add_f32_dpp v49, v49, v49 row_ror:8 row_mask:0xf bank_mask:0xf bound_ctrl:1
	v_mul_f32_e32 v53, v48, v37
	v_add_f32_dpp v26, v26, v26 row_ror:8 row_mask:0xf bank_mask:0xf bound_ctrl:1
	ds_read_b128 v[4:7], v158 offset:0
	v_mul_f32_e32 v54, v48, v38
	ds_read_b128 v[8:11], v158 offset:16
	v_add_f32_dpp v49, v49, v49 row_ror:4 row_mask:0xf bank_mask:0xf bound_ctrl:1
	v_mul_f32_e32 v55, v48, v39
	v_add_f32_dpp v26, v26, v26 row_ror:4 row_mask:0xf bank_mask:0xf bound_ctrl:1
	ds_read_b128 v[12:15], v158 offset:32
	v_fma_f32 v56, v68, v44, v52
	ds_read_b128 v[20:23], v158 offset:64
	v_add_f32_dpp v49, v49, v49 row_ror:2 row_mask:0xf bank_mask:0xf bound_ctrl:1
	v_fma_f32 v57, v69, v45, v53
	v_add_f32_dpp v26, v26, v26 row_ror:2 row_mask:0xf bank_mask:0xf bound_ctrl:1
	ds_read_u16_d16_hi v24, v159 offset:0
	v_fma_f32 v58, v70, v46, v54
	v_add_f32_dpp v49, v49, v49 row_ror:1 row_mask:0xf bank_mask:0xf bound_ctrl:1
	v_fma_f32 v59, v71, v47, v55
	v_add_f32_dpp v26, v26, v26 row_ror:1 row_mask:0xf bank_mask:0xf bound_ctrl:1
	s_nop 0
	v_fma_f32 v68, -v49, v32, v56
	v_fma_f32 v69, -v49, v33, v57
	v_fma_f32 v70, -v49, v34, v58
	v_fma_f32 v71, -v49, v35, v59
	v_cndmask_b32_e64 v60, v60, v26, s[34:35]
	s_waitcnt lgkmcnt(0)
	s_barrier
; DEVI void rw_chain_task(const Params& p, int l, int seq, int head, int quarter, char* smem) {
;     ...
;       lds_barrier();
;       RW_STORE(R2, B0);
;       RW_LOAD(R2, c + 6);
;       RW_COMPUTE(B1, c + 1);
	s_mov_b32 vcc_lo, s42
	s_mov_b32 s42, s43
	s_mov_b32 s43, s45
	s_mov_b32 s45, vcc_lo
	v_add_u32_e32 v156, s42, v162
	v_add_u32_e32 v157, s42, v163
	v_add_u32_e32 v155, s45, v164
	v_add_u32_e32 v165, s45, v167
	v_add_u32_e32 v166, s45, v168
	s_waitcnt lgkmcnt(0)
	v_mul_f32_e32 v25, v68, v4
	v_mul_f32_e32 v50, v68, v40
	v_fmac_f32_e32 v25, v69, v5
	v_fmac_f32_e32 v50, v69, v41
	v_fmac_f32_e32 v25, v70, v6
	v_fmac_f32_e32 v50, v70, v42
	v_fmac_f32_e32 v25, v71, v7
	v_fmac_f32_e32 v50, v71, v43
	v_mul_f32_e32 v52, v24, v12
	ds_read_b128 v[40:43], v156 offset:1456
	v_add_f32_dpp v25, v25, v25 row_ror:8 row_mask:0xf bank_mask:0xf bound_ctrl:1
	v_mul_f32_e32 v53, v24, v13
	v_add_f32_dpp v50, v50, v50 row_ror:8 row_mask:0xf bank_mask:0xf bound_ctrl:1
	ds_read_b128 v[28:31], v156 offset:1408
	v_mul_f32_e32 v54, v24, v14
	ds_read_b128 v[32:35], v156 offset:1424
	v_add_f32_dpp v25, v25, v25 row_ror:4 row_mask:0xf bank_mask:0xf bound_ctrl:1
	v_mul_f32_e32 v55, v24, v15
	v_add_f32_dpp v50, v50, v50 row_ror:4 row_mask:0xf bank_mask:0xf bound_ctrl:1
	ds_read_b128 v[36:39], v156 offset:1440
	v_fma_f32 v56, v68, v20, v52
	ds_read_b128 v[44:47], v156 offset:1472
	v_add_f32_dpp v25, v25, v25 row_ror:2 row_mask:0xf bank_mask:0xf bound_ctrl:1
	v_fma_f32 v57, v69, v21, v53
	v_add_f32_dpp v50, v50, v50 row_ror:2 row_mask:0xf bank_mask:0xf bound_ctrl:1
	ds_read_u16_d16_hi v48, v157 offset:1408
	v_fma_f32 v58, v70, v22, v54
	v_add_f32_dpp v25, v25, v25 row_ror:1 row_mask:0xf bank_mask:0xf bound_ctrl:1
	v_fma_f32 v59, v71, v23, v55
	v_add_f32_dpp v50, v50, v50 row_ror:1 row_mask:0xf bank_mask:0xf bound_ctrl:1
	s_nop 0
	v_fma_f32 v68, -v25, v8, v56
	v_fma_f32 v69, -v25, v9, v57
	v_fma_f32 v70, -v25, v10, v58
	v_fma_f32 v71, -v25, v11, v59
	v_cndmask_b32_e64 v60, v60, v50, s[36:37]
	v_bfe_u32 v61, v60, 16, 1
	v_add3_u32 v61, v60, v61, s33
	global_store_short_d16_hi v[160:161], v61, off
	v_lshl_add_u64 v[160:161], v[160:161], 0, s[46:47]
	s_waitcnt lgkmcnt(0)
	v_mul_f32_e32 v49, v68, v28
	v_mul_f32_e32 v26, v68, v16
	v_fmac_f32_e32 v49, v69, v29
	v_fmac_f32_e32 v26, v69, v17
	v_fmac_f32_e32 v49, v70, v30
	v_fmac_f32_e32 v26, v70, v18
	v_fmac_f32_e32 v49, v71, v31
	v_fmac_f32_e32 v26, v71, v19
	v_mul_f32_e32 v52, v48, v36
	ds_read_b128 v[16:19], v156 offset:2864
	v_add_f32_dpp v49, v49, v49 row_ror:8 row_mask:0xf bank_mask:0xf bound_ctrl:1
	v_mul_f32_e32 v53, v48, v37
	v_add_f32_dpp v26, v26, v26 row_ror:8 row_mask:0xf bank_mask:0xf bound_ctrl:1
	ds_read_b128 v[4:7], v156 offset:2816
	v_mul_f32_e32 v54, v48, v38
	ds_read_b128 v[8:11], v156 offset:2832
	v_add_f32_dpp v49, v49, v49 row_ror:4 row_mask:0xf bank_mask:0xf bound_ctrl:1
	v_mul_f32_e32 v55, v48, v39
	v_add_f32_dpp v26, v26, v26 row_ror:4 row_mask:0xf bank_mask:0xf bound_ctrl:1
	ds_read_b128 v[12:15], v156 offset:2848
	v_fma_f32 v56, v68, v44, v52
	ds_read_b128 v[20:23], v156 offset:2880
	v_add_f32_dpp v49, v49, v49 row_ror:2 row_mask:0xf bank_mask:0xf bound_ctrl:1
	v_fma_f32 v57, v69, v45, v53
	v_add_f32_dpp v26, v26, v26 row_ror:2 row_mask:0xf bank_mask:0xf bound_ctrl:1
	ds_read_u16_d16_hi v24, v157 offset:2816
	v_fma_f32 v58, v70, v46, v54
	s_waitcnt vmcnt(12)
	v_add_f32_dpp v49, v49, v49 row_ror:1 row_mask:0xf bank_mask:0xf bound_ctrl:1
	v_fma_f32 v59, v71, v47, v55
	v_add_f32_dpp v26, v26, v26 row_ror:1 row_mask:0xf bank_mask:0xf bound_ctrl:1
	v_lshlrev_b32_e32 v136, 16, v120
	s_nop 0
	v_fma_f32 v68, -v49, v32, v56
	v_fma_f32 v69, -v49, v33, v57
	v_fma_f32 v70, -v49, v34, v58
	v_fma_f32 v71, -v49, v35, v59
	v_cndmask_b32_e64 v60, v60, v26, s[4:5]
	v_and_b32_e32 v137, 0xffff0000, v120
	s_waitcnt lgkmcnt(0)
	v_mul_f32_e32 v25, v68, v4
	v_mul_f32_e32 v50, v68, v40
	v_fmac_f32_e32 v25, v69, v5
	v_fmac_f32_e32 v50, v69, v41
	v_fmac_f32_e32 v25, v70, v6
	v_fmac_f32_e32 v50, v70, v42
	v_fmac_f32_e32 v25, v71, v7
	v_fmac_f32_e32 v50, v71, v43
	v_mul_f32_e32 v52, v24, v12
	ds_read_b128 v[40:43], v156 offset:4272
	v_add_f32_dpp v25, v25, v25 row_ror:8 row_mask:0xf bank_mask:0xf bound_ctrl:1
	v_mul_f32_e32 v53, v24, v13
	v_add_f32_dpp v50, v50, v50 row_ror:8 row_mask:0xf bank_mask:0xf bound_ctrl:1
	ds_read_b128 v[28:31], v156 offset:4224
	v_mul_f32_e32 v54, v24, v14
	ds_read_b128 v[32:35], v156 offset:4240
	v_add_f32_dpp v25, v25, v25 row_ror:4 row_mask:0xf bank_mask:0xf bound_ctrl:1
	v_mul_f32_e32 v55, v24, v15
	v_add_f32_dpp v50, v50, v50 row_ror:4 row_mask:0xf bank_mask:0xf bound_ctrl:1
	ds_read_b128 v[36:39], v156 offset:4256
	v_fma_f32 v56, v68, v20, v52
	ds_read_b128 v[44:47], v156 offset:4288
	v_add_f32_dpp v25, v25, v25 row_ror:2 row_mask:0xf bank_mask:0xf bound_ctrl:1
	v_fma_f32 v57, v69, v21, v53
	v_add_f32_dpp v50, v50, v50 row_ror:2 row_mask:0xf bank_mask:0xf bound_ctrl:1
	ds_read_u16_d16_hi v48, v157 offset:4224
	v_fma_f32 v58, v70, v22, v54
	v_lshlrev_b32_e32 v138, 16, v121
	v_add_f32_dpp v25, v25, v25 row_ror:1 row_mask:0xf bank_mask:0xf bound_ctrl:1
	v_fma_f32 v59, v71, v23, v55
	v_add_f32_dpp v50, v50, v50 row_ror:1 row_mask:0xf bank_mask:0xf bound_ctrl:1
	v_and_b32_e32 v139, 0xffff0000, v121
	s_nop 0
	v_fma_f32 v68, -v25, v8, v56
	v_fma_f32 v69, -v25, v9, v57
	v_fma_f32 v70, -v25, v10, v58
	v_fma_f32 v71, -v25, v11, v59
	v_cndmask_b32_e64 v60, v60, v50, s[6:7]
	v_lshlrev_b32_e32 v140, 16, v122
	s_waitcnt lgkmcnt(0)
	v_mul_f32_e32 v49, v68, v28
	v_mul_f32_e32 v26, v68, v16
	v_fmac_f32_e32 v49, v69, v29
	v_fmac_f32_e32 v26, v69, v17
	v_fmac_f32_e32 v49, v70, v30
	v_fmac_f32_e32 v26, v70, v18
	v_fmac_f32_e32 v49, v71, v31
	v_fmac_f32_e32 v26, v71, v19
	v_mul_f32_e32 v52, v48, v36
	ds_read_b128 v[16:19], v156 offset:5680
	v_add_f32_dpp v49, v49, v49 row_ror:8 row_mask:0xf bank_mask:0xf bound_ctrl:1
	v_mul_f32_e32 v53, v48, v37
	v_add_f32_dpp v26, v26, v26 row_ror:8 row_mask:0xf bank_mask:0xf bound_ctrl:1
	ds_read_b128 v[4:7], v156 offset:5632
	v_mul_f32_e32 v54, v48, v38
	ds_read_b128 v[8:11], v156 offset:5648
	v_add_f32_dpp v49, v49, v49 row_ror:4 row_mask:0xf bank_mask:0xf bound_ctrl:1
	v_mul_f32_e32 v55, v48, v39
	v_add_f32_dpp v26, v26, v26 row_ror:4 row_mask:0xf bank_mask:0xf bound_ctrl:1
	ds_read_b128 v[12:15], v156 offset:5664
	v_fma_f32 v56, v68, v44, v52
	ds_read_b128 v[20:23], v156 offset:5696
	v_add_f32_dpp v49, v49, v49 row_ror:2 row_mask:0xf bank_mask:0xf bound_ctrl:1
	v_fma_f32 v57, v69, v45, v53
	v_add_f32_dpp v26, v26, v26 row_ror:2 row_mask:0xf bank_mask:0xf bound_ctrl:1
	ds_read_u16_d16_hi v24, v157 offset:5632
	v_fma_f32 v58, v70, v46, v54
	v_and_b32_e32 v141, 0xffff0000, v122
	v_add_f32_dpp v49, v49, v49 row_ror:1 row_mask:0xf bank_mask:0xf bound_ctrl:1
	v_fma_f32 v59, v71, v47, v55
	v_add_f32_dpp v26, v26, v26 row_ror:1 row_mask:0xf bank_mask:0xf bound_ctrl:1
	v_lshlrev_b32_e32 v142, 16, v123
	s_nop 0
	v_fma_f32 v68, -v49, v32, v56
	v_fma_f32 v69, -v49, v33, v57
	v_fma_f32 v70, -v49, v34, v58
	v_fma_f32 v71, -v49, v35, v59
	v_cndmask_b32_e64 v60, v60, v26, s[8:9]
	v_and_b32_e32 v143, 0xffff0000, v123
	s_waitcnt lgkmcnt(0)
	v_mul_f32_e32 v25, v68, v4
	v_mul_f32_e32 v50, v68, v40
	v_fmac_f32_e32 v25, v69, v5
	v_fmac_f32_e32 v50, v69, v41
	v_fmac_f32_e32 v25, v70, v6
	v_fmac_f32_e32 v50, v70, v42
	v_fmac_f32_e32 v25, v71, v7
	v_fmac_f32_e32 v50, v71, v43
	v_mul_f32_e32 v52, v24, v12
	ds_read_b128 v[40:43], v156 offset:7088
	v_add_f32_dpp v25, v25, v25 row_ror:8 row_mask:0xf bank_mask:0xf bound_ctrl:1
	v_mul_f32_e32 v53, v24, v13
	v_add_f32_dpp v50, v50, v50 row_ror:8 row_mask:0xf bank_mask:0xf bound_ctrl:1
	ds_read_b128 v[28:31], v156 offset:7040
	v_mul_f32_e32 v54, v24, v14
	ds_read_b128 v[32:35], v156 offset:7056
	v_add_f32_dpp v25, v25, v25 row_ror:4 row_mask:0xf bank_mask:0xf bound_ctrl:1
	v_mul_f32_e32 v55, v24, v15
	v_add_f32_dpp v50, v50, v50 row_ror:4 row_mask:0xf bank_mask:0xf bound_ctrl:1
	ds_read_b128 v[36:39], v156 offset:7072
	v_fma_f32 v56, v68, v20, v52
	ds_read_b128 v[44:47], v156 offset:7104
	v_add_f32_dpp v25, v25, v25 row_ror:2 row_mask:0xf bank_mask:0xf bound_ctrl:1
	v_fma_f32 v57, v69, v21, v53
	v_add_f32_dpp v50, v50, v50 row_ror:2 row_mask:0xf bank_mask:0xf bound_ctrl:1
	ds_read_u16_d16_hi v48, v157 offset:7040
	v_fma_f32 v58, v70, v22, v54
	ds_write_b128 v155, v[136:139] offset:0
	v_add_f32_dpp v25, v25, v25 row_ror:1 row_mask:0xf bank_mask:0xf bound_ctrl:1
	v_fma_f32 v59, v71, v23, v55
	v_add_f32_dpp v50, v50, v50 row_ror:1 row_mask:0xf bank_mask:0xf bound_ctrl:1
	ds_write_b128 v155, v[140:143] offset:80
	s_nop 0
	v_fma_f32 v68, -v25, v8, v56
	v_fma_f32 v69, -v25, v9, v57
	v_fma_f32 v70, -v25, v10, v58
	v_fma_f32 v71, -v25, v11, v59
	v_cndmask_b32_e64 v60, v60, v50, s[10:11]
	v_lshlrev_b32_e32 v136, 16, v124
	s_waitcnt lgkmcnt(0)
	v_mul_f32_e32 v49, v68, v28
	v_mul_f32_e32 v26, v68, v16
	v_fmac_f32_e32 v49, v69, v29
	v_fmac_f32_e32 v26, v69, v17
	v_fmac_f32_e32 v49, v70, v30
	v_fmac_f32_e32 v26, v70, v18
	v_fmac_f32_e32 v49, v71, v31
	v_fmac_f32_e32 v26, v71, v19
	v_mul_f32_e32 v52, v48, v36
	ds_read_b128 v[16:19], v156 offset:8496
	v_add_f32_dpp v49, v49, v49 row_ror:8 row_mask:0xf bank_mask:0xf bound_ctrl:1
	v_mul_f32_e32 v53, v48, v37
	v_add_f32_dpp v26, v26, v26 row_ror:8 row_mask:0xf bank_mask:0xf bound_ctrl:1
	ds_read_b128 v[4:7], v156 offset:8448
	v_mul_f32_e32 v54, v48, v38
	ds_read_b128 v[8:11], v156 offset:8464
	v_add_f32_dpp v49, v49, v49 row_ror:4 row_mask:0xf bank_mask:0xf bound_ctrl:1
	v_mul_f32_e32 v55, v48, v39
	v_add_f32_dpp v26, v26, v26 row_ror:4 row_mask:0xf bank_mask:0xf bound_ctrl:1
	ds_read_b128 v[12:15], v156 offset:8480
	v_fma_f32 v56, v68, v44, v52
	ds_read_b128 v[20:23], v156 offset:8512
	v_add_f32_dpp v49, v49, v49 row_ror:2 row_mask:0xf bank_mask:0xf bound_ctrl:1
	v_fma_f32 v57, v69, v45, v53
	v_add_f32_dpp v26, v26, v26 row_ror:2 row_mask:0xf bank_mask:0xf bound_ctrl:1
	ds_read_u16_d16_hi v24, v157 offset:8448
	v_fma_f32 v58, v70, v46, v54
	v_and_b32_e32 v137, 0xffff0000, v124
	v_add_f32_dpp v49, v49, v49 row_ror:1 row_mask:0xf bank_mask:0xf bound_ctrl:1
	v_fma_f32 v59, v71, v47, v55
	v_add_f32_dpp v26, v26, v26 row_ror:1 row_mask:0xf bank_mask:0xf bound_ctrl:1
	v_lshlrev_b32_e32 v138, 16, v125
	s_nop 0
	v_fma_f32 v68, -v49, v32, v56
	v_fma_f32 v69, -v49, v33, v57
	v_fma_f32 v70, -v49, v34, v58
	v_fma_f32 v71, -v49, v35, v59
	v_cndmask_b32_e64 v60, v60, v26, s[12:13]
	v_and_b32_e32 v139, 0xffff0000, v125
	s_waitcnt lgkmcnt(0)
	v_mul_f32_e32 v25, v68, v4
	v_mul_f32_e32 v50, v68, v40
	v_fmac_f32_e32 v25, v69, v5
	v_fmac_f32_e32 v50, v69, v41
	v_fmac_f32_e32 v25, v70, v6
	v_fmac_f32_e32 v50, v70, v42
	v_fmac_f32_e32 v25, v71, v7
	v_fmac_f32_e32 v50, v71, v43
	v_mul_f32_e32 v52, v24, v12
	ds_read_b128 v[40:43], v156 offset:9904
	v_add_f32_dpp v25, v25, v25 row_ror:8 row_mask:0xf bank_mask:0xf bound_ctrl:1
	v_mul_f32_e32 v53, v24, v13
	v_add_f32_dpp v50, v50, v50 row_ror:8 row_mask:0xf bank_mask:0xf bound_ctrl:1
	ds_read_b128 v[28:31], v156 offset:9856
	v_mul_f32_e32 v54, v24, v14
	ds_read_b128 v[32:35], v156 offset:9872
	v_add_f32_dpp v25, v25, v25 row_ror:4 row_mask:0xf bank_mask:0xf bound_ctrl:1
	v_mul_f32_e32 v55, v24, v15
	v_add_f32_dpp v50, v50, v50 row_ror:4 row_mask:0xf bank_mask:0xf bound_ctrl:1
	ds_read_b128 v[36:39], v156 offset:9888
	v_fma_f32 v56, v68, v20, v52
	ds_read_b128 v[44:47], v156 offset:9920
	v_add_f32_dpp v25, v25, v25 row_ror:2 row_mask:0xf bank_mask:0xf bound_ctrl:1
	v_fma_f32 v57, v69, v21, v53
	v_add_f32_dpp v50, v50, v50 row_ror:2 row_mask:0xf bank_mask:0xf bound_ctrl:1
	ds_read_u16_d16_hi v48, v157 offset:9856
	v_fma_f32 v58, v70, v22, v54
	v_lshlrev_b32_e32 v140, 16, v126
	v_add_f32_dpp v25, v25, v25 row_ror:1 row_mask:0xf bank_mask:0xf bound_ctrl:1
	v_fma_f32 v59, v71, v23, v55
	v_add_f32_dpp v50, v50, v50 row_ror:1 row_mask:0xf bank_mask:0xf bound_ctrl:1
	v_and_b32_e32 v141, 0xffff0000, v126
	s_nop 0
	v_fma_f32 v68, -v25, v8, v56
	v_fma_f32 v69, -v25, v9, v57
	v_fma_f32 v70, -v25, v10, v58
	v_fma_f32 v71, -v25, v11, v59
	v_cndmask_b32_e64 v60, v60, v50, s[14:15]
	v_lshlrev_b32_e32 v142, 16, v127
	s_waitcnt lgkmcnt(0)
	v_mul_f32_e32 v49, v68, v28
	v_mul_f32_e32 v26, v68, v16
	v_fmac_f32_e32 v49, v69, v29
	v_fmac_f32_e32 v26, v69, v17
	v_fmac_f32_e32 v49, v70, v30
	v_fmac_f32_e32 v26, v70, v18
	v_fmac_f32_e32 v49, v71, v31
	v_fmac_f32_e32 v26, v71, v19
	v_mul_f32_e32 v52, v48, v36
	ds_read_b128 v[16:19], v156 offset:11312
	v_add_f32_dpp v49, v49, v49 row_ror:8 row_mask:0xf bank_mask:0xf bound_ctrl:1
	v_mul_f32_e32 v53, v48, v37
	v_add_f32_dpp v26, v26, v26 row_ror:8 row_mask:0xf bank_mask:0xf bound_ctrl:1
	ds_read_b128 v[4:7], v156 offset:11264
	v_mul_f32_e32 v54, v48, v38
	ds_read_b128 v[8:11], v156 offset:11280
	v_add_f32_dpp v49, v49, v49 row_ror:4 row_mask:0xf bank_mask:0xf bound_ctrl:1
	v_mul_f32_e32 v55, v48, v39
	v_add_f32_dpp v26, v26, v26 row_ror:4 row_mask:0xf bank_mask:0xf bound_ctrl:1
	ds_read_b128 v[12:15], v156 offset:11296
	v_fma_f32 v56, v68, v44, v52
	ds_read_b128 v[20:23], v156 offset:11328
	v_add_f32_dpp v49, v49, v49 row_ror:2 row_mask:0xf bank_mask:0xf bound_ctrl:1
	v_fma_f32 v57, v69, v45, v53
	v_add_f32_dpp v26, v26, v26 row_ror:2 row_mask:0xf bank_mask:0xf bound_ctrl:1
	ds_read_u16_d16_hi v24, v157 offset:11264
	v_fma_f32 v58, v70, v46, v54
	v_and_b32_e32 v143, 0xffff0000, v127
	v_add_f32_dpp v49, v49, v49 row_ror:1 row_mask:0xf bank_mask:0xf bound_ctrl:1
	v_fma_f32 v59, v71, v47, v55
	v_add_f32_dpp v26, v26, v26 row_ror:1 row_mask:0xf bank_mask:0xf bound_ctrl:1
	ds_write_b128 v155, v[136:139] offset:11264
	s_nop 0
	v_fma_f32 v68, -v49, v32, v56
	v_fma_f32 v69, -v49, v33, v57
	v_fma_f32 v70, -v49, v34, v58
	v_fma_f32 v71, -v49, v35, v59
	v_cndmask_b32_e64 v60, v60, v26, s[16:17]
	ds_write_b128 v155, v[140:143] offset:11344
	s_waitcnt lgkmcnt(0)
	v_mul_f32_e32 v25, v68, v4
	v_mul_f32_e32 v50, v68, v40
	v_fmac_f32_e32 v25, v69, v5
	v_fmac_f32_e32 v50, v69, v41
	v_fmac_f32_e32 v25, v70, v6
	v_fmac_f32_e32 v50, v70, v42
	v_fmac_f32_e32 v25, v71, v7
	v_fmac_f32_e32 v50, v71, v43
	v_mul_f32_e32 v52, v24, v12
	ds_read_b128 v[40:43], v156 offset:12720
	v_add_f32_dpp v25, v25, v25 row_ror:8 row_mask:0xf bank_mask:0xf bound_ctrl:1
	v_mul_f32_e32 v53, v24, v13
	v_add_f32_dpp v50, v50, v50 row_ror:8 row_mask:0xf bank_mask:0xf bound_ctrl:1
	ds_read_b128 v[28:31], v156 offset:12672
	v_mul_f32_e32 v54, v24, v14
	ds_read_b128 v[32:35], v156 offset:12688
	v_add_f32_dpp v25, v25, v25 row_ror:4 row_mask:0xf bank_mask:0xf bound_ctrl:1
	v_mul_f32_e32 v55, v24, v15
	v_add_f32_dpp v50, v50, v50 row_ror:4 row_mask:0xf bank_mask:0xf bound_ctrl:1
	ds_read_b128 v[36:39], v156 offset:12704
	v_fma_f32 v56, v68, v20, v52
	ds_read_b128 v[44:47], v156 offset:12736
	v_add_f32_dpp v25, v25, v25 row_ror:2 row_mask:0xf bank_mask:0xf bound_ctrl:1
	v_fma_f32 v57, v69, v21, v53
	v_add_f32_dpp v50, v50, v50 row_ror:2 row_mask:0xf bank_mask:0xf bound_ctrl:1
	ds_read_u16_d16_hi v48, v157 offset:12672
	v_fma_f32 v58, v70, v22, v54
	ds_write_b128 v165, v[128:131]
	v_add_f32_dpp v25, v25, v25 row_ror:1 row_mask:0xf bank_mask:0xf bound_ctrl:1
	v_fma_f32 v59, v71, v23, v55
	v_add_f32_dpp v50, v50, v50 row_ror:1 row_mask:0xf bank_mask:0xf bound_ctrl:1
	ds_write_b128 v166, v[132:135]
	s_nop 0
	v_fma_f32 v68, -v25, v8, v56
	v_fma_f32 v69, -v25, v9, v57
	v_fma_f32 v70, -v25, v10, v58
	v_fma_f32 v71, -v25, v11, v59
	v_cndmask_b32_e64 v60, v60, v50, s[18:19]
	global_load_dwordx4 v[120:123], v[144:145], off
	s_waitcnt lgkmcnt(0)
	v_mul_f32_e32 v49, v68, v28
	v_mul_f32_e32 v26, v68, v16
	v_fmac_f32_e32 v49, v69, v29
	v_fmac_f32_e32 v26, v69, v17
	v_fmac_f32_e32 v49, v70, v30
	v_fmac_f32_e32 v26, v70, v18
	v_fmac_f32_e32 v49, v71, v31
	v_fmac_f32_e32 v26, v71, v19
	v_mul_f32_e32 v52, v48, v36
	ds_read_b128 v[16:19], v156 offset:14128
	v_add_f32_dpp v49, v49, v49 row_ror:8 row_mask:0xf bank_mask:0xf bound_ctrl:1
	v_mul_f32_e32 v53, v48, v37
	v_add_f32_dpp v26, v26, v26 row_ror:8 row_mask:0xf bank_mask:0xf bound_ctrl:1
	ds_read_b128 v[4:7], v156 offset:14080
	v_mul_f32_e32 v54, v48, v38
	ds_read_b128 v[8:11], v156 offset:14096
	v_add_f32_dpp v49, v49, v49 row_ror:4 row_mask:0xf bank_mask:0xf bound_ctrl:1
	v_mul_f32_e32 v55, v48, v39
	v_add_f32_dpp v26, v26, v26 row_ror:4 row_mask:0xf bank_mask:0xf bound_ctrl:1
	ds_read_b128 v[12:15], v156 offset:14112
	v_fma_f32 v56, v68, v44, v52
	ds_read_b128 v[20:23], v156 offset:14144
	v_add_f32_dpp v49, v49, v49 row_ror:2 row_mask:0xf bank_mask:0xf bound_ctrl:1
	v_fma_f32 v57, v69, v45, v53
	v_add_f32_dpp v26, v26, v26 row_ror:2 row_mask:0xf bank_mask:0xf bound_ctrl:1
	ds_read_u16_d16_hi v24, v157 offset:14080
	v_fma_f32 v58, v70, v46, v54
	global_load_dwordx4 v[124:127], v[146:147], off
	v_add_f32_dpp v49, v49, v49 row_ror:1 row_mask:0xf bank_mask:0xf bound_ctrl:1
	v_fma_f32 v59, v71, v47, v55
	v_add_f32_dpp v26, v26, v26 row_ror:1 row_mask:0xf bank_mask:0xf bound_ctrl:1
	global_load_dwordx4 v[128:131], v[148:149], off
	s_nop 0
	v_fma_f32 v68, -v49, v32, v56
	v_fma_f32 v69, -v49, v33, v57
	v_fma_f32 v70, -v49, v34, v58
	v_fma_f32 v71, -v49, v35, v59
	v_cndmask_b32_e64 v60, v60, v26, s[20:21]
	global_load_dwordx4 v[132:135], v[150:151], off
	s_waitcnt lgkmcnt(0)
	v_mul_f32_e32 v25, v68, v4
	v_mul_f32_e32 v50, v68, v40
	v_fmac_f32_e32 v25, v69, v5
	v_fmac_f32_e32 v50, v69, v41
	v_fmac_f32_e32 v25, v70, v6
	v_fmac_f32_e32 v50, v70, v42
	v_fmac_f32_e32 v25, v71, v7
	v_fmac_f32_e32 v50, v71, v43
	v_mul_f32_e32 v52, v24, v12
	ds_read_b128 v[40:43], v156 offset:15536
	v_add_f32_dpp v25, v25, v25 row_ror:8 row_mask:0xf bank_mask:0xf bound_ctrl:1
	v_mul_f32_e32 v53, v24, v13
	v_add_f32_dpp v50, v50, v50 row_ror:8 row_mask:0xf bank_mask:0xf bound_ctrl:1
	ds_read_b128 v[28:31], v156 offset:15488
	v_mul_f32_e32 v54, v24, v14
	ds_read_b128 v[32:35], v156 offset:15504
	v_add_f32_dpp v25, v25, v25 row_ror:4 row_mask:0xf bank_mask:0xf bound_ctrl:1
	v_mul_f32_e32 v55, v24, v15
	v_add_f32_dpp v50, v50, v50 row_ror:4 row_mask:0xf bank_mask:0xf bound_ctrl:1
	ds_read_b128 v[36:39], v156 offset:15520
	v_fma_f32 v56, v68, v20, v52
	ds_read_b128 v[44:47], v156 offset:15552
	v_add_f32_dpp v25, v25, v25 row_ror:2 row_mask:0xf bank_mask:0xf bound_ctrl:1
	v_fma_f32 v57, v69, v21, v53
	v_add_f32_dpp v50, v50, v50 row_ror:2 row_mask:0xf bank_mask:0xf bound_ctrl:1
	ds_read_u16_d16_hi v48, v157 offset:15488
	v_fma_f32 v58, v70, v22, v54
	v_lshl_add_u64 v[144:145], v[144:145], 0, v[152:153]
	v_add_f32_dpp v25, v25, v25 row_ror:1 row_mask:0xf bank_mask:0xf bound_ctrl:1
	v_fma_f32 v59, v71, v23, v55
	v_add_f32_dpp v50, v50, v50 row_ror:1 row_mask:0xf bank_mask:0xf bound_ctrl:1
	v_lshl_add_u64 v[146:147], v[146:147], 0, v[152:153]
	s_nop 0
	v_fma_f32 v68, -v25, v8, v56
	v_fma_f32 v69, -v25, v9, v57
	v_fma_f32 v70, -v25, v10, v58
	v_fma_f32 v71, -v25, v11, v59
	v_cndmask_b32_e64 v60, v60, v50, s[22:23]
	v_lshl_add_u64 v[148:149], v[148:149], 0, v[62:63]
	s_waitcnt lgkmcnt(0)
	v_mul_f32_e32 v49, v68, v28
	v_mul_f32_e32 v26, v68, v16
	v_fmac_f32_e32 v49, v69, v29
	v_fmac_f32_e32 v26, v69, v17
	v_fmac_f32_e32 v49, v70, v30
	v_fmac_f32_e32 v26, v70, v18
	v_fmac_f32_e32 v49, v71, v31
	v_fmac_f32_e32 v26, v71, v19
	v_mul_f32_e32 v52, v48, v36
	ds_read_b128 v[16:19], v156 offset:16944
	v_add_f32_dpp v49, v49, v49 row_ror:8 row_mask:0xf bank_mask:0xf bound_ctrl:1
	v_mul_f32_e32 v53, v48, v37
	v_add_f32_dpp v26, v26, v26 row_ror:8 row_mask:0xf bank_mask:0xf bound_ctrl:1
	ds_read_b128 v[4:7], v156 offset:16896
	v_mul_f32_e32 v54, v48, v38
	ds_read_b128 v[8:11], v156 offset:16912
	v_add_f32_dpp v49, v49, v49 row_ror:4 row_mask:0xf bank_mask:0xf bound_ctrl:1
	v_mul_f32_e32 v55, v48, v39
	v_add_f32_dpp v26, v26, v26 row_ror:4 row_mask:0xf bank_mask:0xf bound_ctrl:1
	ds_read_b128 v[12:15], v156 offset:16928
	v_fma_f32 v56, v68, v44, v52
	ds_read_b128 v[20:23], v156 offset:16960
	v_add_f32_dpp v49, v49, v49 row_ror:2 row_mask:0xf bank_mask:0xf bound_ctrl:1
	v_fma_f32 v57, v69, v45, v53
	v_add_f32_dpp v26, v26, v26 row_ror:2 row_mask:0xf bank_mask:0xf bound_ctrl:1
	ds_read_u16_d16_hi v24, v157 offset:16896
	v_fma_f32 v58, v70, v46, v54
	v_lshl_add_u64 v[150:151], v[150:151], 0, v[64:65]
	v_add_f32_dpp v49, v49, v49 row_ror:1 row_mask:0xf bank_mask:0xf bound_ctrl:1
	v_fma_f32 v59, v71, v47, v55
	v_add_f32_dpp v26, v26, v26 row_ror:1 row_mask:0xf bank_mask:0xf bound_ctrl:1
	v_add_u32_e32 v158, s43, v162
	s_nop 0
	v_fma_f32 v68, -v49, v32, v56
	v_fma_f32 v69, -v49, v33, v57
	v_fma_f32 v70, -v49, v34, v58
	v_fma_f32 v71, -v49, v35, v59
	v_cndmask_b32_e64 v60, v60, v26, s[24:25]
	v_add_u32_e32 v159, s43, v163
	s_waitcnt lgkmcnt(0)
; DEVI void rw_chain_task(const Params& p, int l, int seq, int head, int quarter, char* smem) {
;     ...
;       lds_barrier();
;       RW_STORE(R2, B0);
;       RW_LOAD(R2, c + 6);
;       RW_COMPUTE(B1, c + 1);
;       lds_barrier();
	v_mul_f32_e32 v25, v68, v4
	v_mul_f32_e32 v50, v68, v40
	v_fmac_f32_e32 v25, v69, v5
	v_fmac_f32_e32 v50, v69, v41
	v_fmac_f32_e32 v25, v70, v6
	v_fmac_f32_e32 v50, v70, v42
	v_fmac_f32_e32 v25, v71, v7
	v_fmac_f32_e32 v50, v71, v43
	v_mul_f32_e32 v52, v24, v12
	ds_read_b128 v[40:43], v156 offset:18352
	v_add_f32_dpp v25, v25, v25 row_ror:8 row_mask:0xf bank_mask:0xf bound_ctrl:1
	v_mul_f32_e32 v53, v24, v13
	v_add_f32_dpp v50, v50, v50 row_ror:8 row_mask:0xf bank_mask:0xf bound_ctrl:1
	ds_read_b128 v[28:31], v156 offset:18304
	v_mul_f32_e32 v54, v24, v14
	ds_read_b128 v[32:35], v156 offset:18320
	v_add_f32_dpp v25, v25, v25 row_ror:4 row_mask:0xf bank_mask:0xf bound_ctrl:1
	v_mul_f32_e32 v55, v24, v15
	v_add_f32_dpp v50, v50, v50 row_ror:4 row_mask:0xf bank_mask:0xf bound_ctrl:1
	ds_read_b128 v[36:39], v156 offset:18336
	v_fma_f32 v56, v68, v20, v52
	ds_read_b128 v[44:47], v156 offset:18368
	v_add_f32_dpp v25, v25, v25 row_ror:2 row_mask:0xf bank_mask:0xf bound_ctrl:1
	v_fma_f32 v57, v69, v21, v53
	v_add_f32_dpp v50, v50, v50 row_ror:2 row_mask:0xf bank_mask:0xf bound_ctrl:1
	ds_read_u16_d16_hi v48, v157 offset:18304
	v_fma_f32 v58, v70, v22, v54
	v_add_f32_dpp v25, v25, v25 row_ror:1 row_mask:0xf bank_mask:0xf bound_ctrl:1
	v_fma_f32 v59, v71, v23, v55
	v_add_f32_dpp v50, v50, v50 row_ror:1 row_mask:0xf bank_mask:0xf bound_ctrl:1
	s_nop 0
	v_fma_f32 v68, -v25, v8, v56
	v_fma_f32 v69, -v25, v9, v57
	v_fma_f32 v70, -v25, v10, v58
	v_fma_f32 v71, -v25, v11, v59
	v_cndmask_b32_e64 v60, v60, v50, s[26:27]
	s_waitcnt lgkmcnt(0)
	v_mul_f32_e32 v49, v68, v28
	v_mul_f32_e32 v26, v68, v16
	v_fmac_f32_e32 v49, v69, v29
	v_fmac_f32_e32 v26, v69, v17
	v_fmac_f32_e32 v49, v70, v30
	v_fmac_f32_e32 v26, v70, v18
	v_fmac_f32_e32 v49, v71, v31
	v_fmac_f32_e32 v26, v71, v19
	v_mul_f32_e32 v52, v48, v36
	ds_read_b128 v[16:19], v156 offset:19760
	v_add_f32_dpp v49, v49, v49 row_ror:8 row_mask:0xf bank_mask:0xf bound_ctrl:1
	v_mul_f32_e32 v53, v48, v37
	v_add_f32_dpp v26, v26, v26 row_ror:8 row_mask:0xf bank_mask:0xf bound_ctrl:1
	ds_read_b128 v[4:7], v156 offset:19712
	v_mul_f32_e32 v54, v48, v38
	ds_read_b128 v[8:11], v156 offset:19728
	v_add_f32_dpp v49, v49, v49 row_ror:4 row_mask:0xf bank_mask:0xf bound_ctrl:1
	v_mul_f32_e32 v55, v48, v39
	v_add_f32_dpp v26, v26, v26 row_ror:4 row_mask:0xf bank_mask:0xf bound_ctrl:1
	ds_read_b128 v[12:15], v156 offset:19744
	v_fma_f32 v56, v68, v44, v52
	ds_read_b128 v[20:23], v156 offset:19776
	v_add_f32_dpp v49, v49, v49 row_ror:2 row_mask:0xf bank_mask:0xf bound_ctrl:1
	v_fma_f32 v57, v69, v45, v53
	v_add_f32_dpp v26, v26, v26 row_ror:2 row_mask:0xf bank_mask:0xf bound_ctrl:1
	ds_read_u16_d16_hi v24, v157 offset:19712
	v_fma_f32 v58, v70, v46, v54
	v_add_f32_dpp v49, v49, v49 row_ror:1 row_mask:0xf bank_mask:0xf bound_ctrl:1
	v_fma_f32 v59, v71, v47, v55
	v_add_f32_dpp v26, v26, v26 row_ror:1 row_mask:0xf bank_mask:0xf bound_ctrl:1
	s_nop 0
	v_fma_f32 v68, -v49, v32, v56
	v_fma_f32 v69, -v49, v33, v57
	v_fma_f32 v70, -v49, v34, v58
	v_fma_f32 v71, -v49, v35, v59
	v_cndmask_b32_e64 v60, v60, v26, s[28:29]
	s_waitcnt lgkmcnt(0)
	v_mul_f32_e32 v25, v68, v4
	v_mul_f32_e32 v50, v68, v40
	v_fmac_f32_e32 v25, v69, v5
	v_fmac_f32_e32 v50, v69, v41
	v_fmac_f32_e32 v25, v70, v6
	v_fmac_f32_e32 v50, v70, v42
	v_fmac_f32_e32 v25, v71, v7
	v_fmac_f32_e32 v50, v71, v43
	v_mul_f32_e32 v52, v24, v12
	ds_read_b128 v[40:43], v156 offset:21168
	v_add_f32_dpp v25, v25, v25 row_ror:8 row_mask:0xf bank_mask:0xf bound_ctrl:1
	v_mul_f32_e32 v53, v24, v13
	v_add_f32_dpp v50, v50, v50 row_ror:8 row_mask:0xf bank_mask:0xf bound_ctrl:1
	ds_read_b128 v[28:31], v156 offset:21120
	v_mul_f32_e32 v54, v24, v14
	ds_read_b128 v[32:35], v156 offset:21136
	v_add_f32_dpp v25, v25, v25 row_ror:4 row_mask:0xf bank_mask:0xf bound_ctrl:1
	v_mul_f32_e32 v55, v24, v15
	v_add_f32_dpp v50, v50, v50 row_ror:4 row_mask:0xf bank_mask:0xf bound_ctrl:1
	ds_read_b128 v[36:39], v156 offset:21152
	v_fma_f32 v56, v68, v20, v52
	ds_read_b128 v[44:47], v156 offset:21184
	v_add_f32_dpp v25, v25, v25 row_ror:2 row_mask:0xf bank_mask:0xf bound_ctrl:1
	v_fma_f32 v57, v69, v21, v53
	v_add_f32_dpp v50, v50, v50 row_ror:2 row_mask:0xf bank_mask:0xf bound_ctrl:1
	ds_read_u16_d16_hi v48, v157 offset:21120
	v_fma_f32 v58, v70, v22, v54
	v_add_f32_dpp v25, v25, v25 row_ror:1 row_mask:0xf bank_mask:0xf bound_ctrl:1
	v_fma_f32 v59, v71, v23, v55
	v_add_f32_dpp v50, v50, v50 row_ror:1 row_mask:0xf bank_mask:0xf bound_ctrl:1
	s_nop 0
	v_fma_f32 v68, -v25, v8, v56
	v_fma_f32 v69, -v25, v9, v57
	v_fma_f32 v70, -v25, v10, v58
	v_fma_f32 v71, -v25, v11, v59
	v_cndmask_b32_e64 v60, v60, v50, s[30:31]
	s_waitcnt lgkmcnt(0)
	v_mul_f32_e32 v49, v68, v28
	v_mul_f32_e32 v26, v68, v16
	v_fmac_f32_e32 v49, v69, v29
	v_fmac_f32_e32 v26, v69, v17
	v_fmac_f32_e32 v49, v70, v30
	v_fmac_f32_e32 v26, v70, v18
	v_fmac_f32_e32 v49, v71, v31
	v_fmac_f32_e32 v26, v71, v19
	v_mul_f32_e32 v52, v48, v36
	ds_read_b128 v[16:19], v158 offset:48
	v_add_f32_dpp v49, v49, v49 row_ror:8 row_mask:0xf bank_mask:0xf bound_ctrl:1
	v_mul_f32_e32 v53, v48, v37
	v_add_f32_dpp v26, v26, v26 row_ror:8 row_mask:0xf bank_mask:0xf bound_ctrl:1
	ds_read_b128 v[4:7], v158 offset:0
	v_mul_f32_e32 v54, v48, v38
	ds_read_b128 v[8:11], v158 offset:16
	v_add_f32_dpp v49, v49, v49 row_ror:4 row_mask:0xf bank_mask:0xf bound_ctrl:1
	v_mul_f32_e32 v55, v48, v39
	v_add_f32_dpp v26, v26, v26 row_ror:4 row_mask:0xf bank_mask:0xf bound_ctrl:1
	ds_read_b128 v[12:15], v158 offset:32
	v_fma_f32 v56, v68, v44, v52
	ds_read_b128 v[20:23], v158 offset:64
	v_add_f32_dpp v49, v49, v49 row_ror:2 row_mask:0xf bank_mask:0xf bound_ctrl:1
	v_fma_f32 v57, v69, v45, v53
	v_add_f32_dpp v26, v26, v26 row_ror:2 row_mask:0xf bank_mask:0xf bound_ctrl:1
	ds_read_u16_d16_hi v24, v159 offset:0
	v_fma_f32 v58, v70, v46, v54
	v_add_f32_dpp v49, v49, v49 row_ror:1 row_mask:0xf bank_mask:0xf bound_ctrl:1
	v_fma_f32 v59, v71, v47, v55
	v_add_f32_dpp v26, v26, v26 row_ror:1 row_mask:0xf bank_mask:0xf bound_ctrl:1
	s_nop 0
	v_fma_f32 v68, -v49, v32, v56
	v_fma_f32 v69, -v49, v33, v57
	v_fma_f32 v70, -v49, v34, v58
	v_fma_f32 v71, -v49, v35, v59
	v_cndmask_b32_e64 v60, v60, v26, s[34:35]
	s_waitcnt lgkmcnt(0)
	s_barrier
; DEVI void rw_chain_task(const Params& p, int l, int seq, int head, int quarter, char* smem) {
;     ...
;       RW_COMPUTE(B1, c + 1);
;       lds_barrier();
;       RW_STORE(R3, B1);
;       RW_LOAD(R3, c + 7);
;       RW_COMPUTE(B0, c + 2);
	s_mov_b32 vcc_lo, s42
	s_mov_b32 s42, s43
	s_mov_b32 s43, s45
	s_mov_b32 s45, vcc_lo
	v_add_u32_e32 v156, s42, v162
	v_add_u32_e32 v157, s42, v163
	v_add_u32_e32 v155, s45, v164
	v_add_u32_e32 v165, s45, v167
	v_add_u32_e32 v166, s45, v168
	s_waitcnt lgkmcnt(0)
	v_mul_f32_e32 v25, v68, v4
	v_mul_f32_e32 v50, v68, v40
	v_fmac_f32_e32 v25, v69, v5
	v_fmac_f32_e32 v50, v69, v41
	v_fmac_f32_e32 v25, v70, v6
	v_fmac_f32_e32 v50, v70, v42
	v_fmac_f32_e32 v25, v71, v7
	v_fmac_f32_e32 v50, v71, v43
	v_mul_f32_e32 v52, v24, v12
	ds_read_b128 v[40:43], v156 offset:1456
	v_add_f32_dpp v25, v25, v25 row_ror:8 row_mask:0xf bank_mask:0xf bound_ctrl:1
	v_mul_f32_e32 v53, v24, v13
	v_add_f32_dpp v50, v50, v50 row_ror:8 row_mask:0xf bank_mask:0xf bound_ctrl:1
	ds_read_b128 v[28:31], v156 offset:1408
	v_mul_f32_e32 v54, v24, v14
	ds_read_b128 v[32:35], v156 offset:1424
	v_add_f32_dpp v25, v25, v25 row_ror:4 row_mask:0xf bank_mask:0xf bound_ctrl:1
	v_mul_f32_e32 v55, v24, v15
	v_add_f32_dpp v50, v50, v50 row_ror:4 row_mask:0xf bank_mask:0xf bound_ctrl:1
	ds_read_b128 v[36:39], v156 offset:1440
	v_fma_f32 v56, v68, v20, v52
	ds_read_b128 v[44:47], v156 offset:1472
	v_add_f32_dpp v25, v25, v25 row_ror:2 row_mask:0xf bank_mask:0xf bound_ctrl:1
	v_fma_f32 v57, v69, v21, v53
	v_add_f32_dpp v50, v50, v50 row_ror:2 row_mask:0xf bank_mask:0xf bound_ctrl:1
	ds_read_u16_d16_hi v48, v157 offset:1408
	v_fma_f32 v58, v70, v22, v54
	v_add_f32_dpp v25, v25, v25 row_ror:1 row_mask:0xf bank_mask:0xf bound_ctrl:1
	v_fma_f32 v59, v71, v23, v55
	v_add_f32_dpp v50, v50, v50 row_ror:1 row_mask:0xf bank_mask:0xf bound_ctrl:1
	s_nop 0
	v_fma_f32 v68, -v25, v8, v56
	v_fma_f32 v69, -v25, v9, v57
	v_fma_f32 v70, -v25, v10, v58
	v_fma_f32 v71, -v25, v11, v59
	v_cndmask_b32_e64 v60, v60, v50, s[36:37]
	v_bfe_u32 v61, v60, 16, 1
	v_add3_u32 v61, v60, v61, s33
	global_store_short_d16_hi v[160:161], v61, off
	v_lshl_add_u64 v[160:161], v[160:161], 0, s[46:47]
	s_waitcnt lgkmcnt(0)
	v_mul_f32_e32 v49, v68, v28
	v_mul_f32_e32 v26, v68, v16
	v_fmac_f32_e32 v49, v69, v29
	v_fmac_f32_e32 v26, v69, v17
	v_fmac_f32_e32 v49, v70, v30
	v_fmac_f32_e32 v26, v70, v18
	v_fmac_f32_e32 v49, v71, v31
	v_fmac_f32_e32 v26, v71, v19
	v_mul_f32_e32 v52, v48, v36
	ds_read_b128 v[16:19], v156 offset:2864
	v_add_f32_dpp v49, v49, v49 row_ror:8 row_mask:0xf bank_mask:0xf bound_ctrl:1
	v_mul_f32_e32 v53, v48, v37
	v_add_f32_dpp v26, v26, v26 row_ror:8 row_mask:0xf bank_mask:0xf bound_ctrl:1
	ds_read_b128 v[4:7], v156 offset:2816
	v_mul_f32_e32 v54, v48, v38
	ds_read_b128 v[8:11], v156 offset:2832
	v_add_f32_dpp v49, v49, v49 row_ror:4 row_mask:0xf bank_mask:0xf bound_ctrl:1
	v_mul_f32_e32 v55, v48, v39
	v_add_f32_dpp v26, v26, v26 row_ror:4 row_mask:0xf bank_mask:0xf bound_ctrl:1
	ds_read_b128 v[12:15], v156 offset:2848
	v_fma_f32 v56, v68, v44, v52
	ds_read_b128 v[20:23], v156 offset:2880
	v_add_f32_dpp v49, v49, v49 row_ror:2 row_mask:0xf bank_mask:0xf bound_ctrl:1
	v_fma_f32 v57, v69, v45, v53
	v_add_f32_dpp v26, v26, v26 row_ror:2 row_mask:0xf bank_mask:0xf bound_ctrl:1
	ds_read_u16_d16_hi v24, v157 offset:2816
	v_fma_f32 v58, v70, v46, v54
	s_waitcnt vmcnt(12)
	v_add_f32_dpp v49, v49, v49 row_ror:1 row_mask:0xf bank_mask:0xf bound_ctrl:1
	v_fma_f32 v59, v71, v47, v55
	v_add_f32_dpp v26, v26, v26 row_ror:1 row_mask:0xf bank_mask:0xf bound_ctrl:1
	v_lshlrev_b32_e32 v136, 16, v72
	s_nop 0
	v_fma_f32 v68, -v49, v32, v56
	v_fma_f32 v69, -v49, v33, v57
	v_fma_f32 v70, -v49, v34, v58
	v_fma_f32 v71, -v49, v35, v59
	v_cndmask_b32_e64 v60, v60, v26, s[4:5]
	v_and_b32_e32 v137, 0xffff0000, v72
	s_waitcnt lgkmcnt(0)
	v_mul_f32_e32 v25, v68, v4
	v_mul_f32_e32 v50, v68, v40
	v_fmac_f32_e32 v25, v69, v5
	v_fmac_f32_e32 v50, v69, v41
	v_fmac_f32_e32 v25, v70, v6
	v_fmac_f32_e32 v50, v70, v42
	v_fmac_f32_e32 v25, v71, v7
	v_fmac_f32_e32 v50, v71, v43
	v_mul_f32_e32 v52, v24, v12
	ds_read_b128 v[40:43], v156 offset:4272
	v_add_f32_dpp v25, v25, v25 row_ror:8 row_mask:0xf bank_mask:0xf bound_ctrl:1
	v_mul_f32_e32 v53, v24, v13
	v_add_f32_dpp v50, v50, v50 row_ror:8 row_mask:0xf bank_mask:0xf bound_ctrl:1
	ds_read_b128 v[28:31], v156 offset:4224
	v_mul_f32_e32 v54, v24, v14
	ds_read_b128 v[32:35], v156 offset:4240
	v_add_f32_dpp v25, v25, v25 row_ror:4 row_mask:0xf bank_mask:0xf bound_ctrl:1
	v_mul_f32_e32 v55, v24, v15
	v_add_f32_dpp v50, v50, v50 row_ror:4 row_mask:0xf bank_mask:0xf bound_ctrl:1
	ds_read_b128 v[36:39], v156 offset:4256
	v_fma_f32 v56, v68, v20, v52
	ds_read_b128 v[44:47], v156 offset:4288
	v_add_f32_dpp v25, v25, v25 row_ror:2 row_mask:0xf bank_mask:0xf bound_ctrl:1
	v_fma_f32 v57, v69, v21, v53
	v_add_f32_dpp v50, v50, v50 row_ror:2 row_mask:0xf bank_mask:0xf bound_ctrl:1
	ds_read_u16_d16_hi v48, v157 offset:4224
	v_fma_f32 v58, v70, v22, v54
	v_lshlrev_b32_e32 v138, 16, v73
	v_add_f32_dpp v25, v25, v25 row_ror:1 row_mask:0xf bank_mask:0xf bound_ctrl:1
	v_fma_f32 v59, v71, v23, v55
	v_add_f32_dpp v50, v50, v50 row_ror:1 row_mask:0xf bank_mask:0xf bound_ctrl:1
	v_and_b32_e32 v139, 0xffff0000, v73
	s_nop 0
	v_fma_f32 v68, -v25, v8, v56
	v_fma_f32 v69, -v25, v9, v57
	v_fma_f32 v70, -v25, v10, v58
	v_fma_f32 v71, -v25, v11, v59
	v_cndmask_b32_e64 v60, v60, v50, s[6:7]
	v_lshlrev_b32_e32 v140, 16, v74
	s_waitcnt lgkmcnt(0)
	v_mul_f32_e32 v49, v68, v28
	v_mul_f32_e32 v26, v68, v16
	v_fmac_f32_e32 v49, v69, v29
	v_fmac_f32_e32 v26, v69, v17
	v_fmac_f32_e32 v49, v70, v30
	v_fmac_f32_e32 v26, v70, v18
	v_fmac_f32_e32 v49, v71, v31
	v_fmac_f32_e32 v26, v71, v19
	v_mul_f32_e32 v52, v48, v36
	ds_read_b128 v[16:19], v156 offset:5680
	v_add_f32_dpp v49, v49, v49 row_ror:8 row_mask:0xf bank_mask:0xf bound_ctrl:1
	v_mul_f32_e32 v53, v48, v37
	v_add_f32_dpp v26, v26, v26 row_ror:8 row_mask:0xf bank_mask:0xf bound_ctrl:1
	ds_read_b128 v[4:7], v156 offset:5632
	v_mul_f32_e32 v54, v48, v38
	ds_read_b128 v[8:11], v156 offset:5648
	v_add_f32_dpp v49, v49, v49 row_ror:4 row_mask:0xf bank_mask:0xf bound_ctrl:1
	v_mul_f32_e32 v55, v48, v39
	v_add_f32_dpp v26, v26, v26 row_ror:4 row_mask:0xf bank_mask:0xf bound_ctrl:1
	ds_read_b128 v[12:15], v156 offset:5664
	v_fma_f32 v56, v68, v44, v52
	ds_read_b128 v[20:23], v156 offset:5696
	v_add_f32_dpp v49, v49, v49 row_ror:2 row_mask:0xf bank_mask:0xf bound_ctrl:1
	v_fma_f32 v57, v69, v45, v53
	v_add_f32_dpp v26, v26, v26 row_ror:2 row_mask:0xf bank_mask:0xf bound_ctrl:1
	ds_read_u16_d16_hi v24, v157 offset:5632
	v_fma_f32 v58, v70, v46, v54
	v_and_b32_e32 v141, 0xffff0000, v74
	v_add_f32_dpp v49, v49, v49 row_ror:1 row_mask:0xf bank_mask:0xf bound_ctrl:1
	v_fma_f32 v59, v71, v47, v55
	v_add_f32_dpp v26, v26, v26 row_ror:1 row_mask:0xf bank_mask:0xf bound_ctrl:1
	v_lshlrev_b32_e32 v142, 16, v75
	s_nop 0
	v_fma_f32 v68, -v49, v32, v56
	v_fma_f32 v69, -v49, v33, v57
	v_fma_f32 v70, -v49, v34, v58
	v_fma_f32 v71, -v49, v35, v59
	v_cndmask_b32_e64 v60, v60, v26, s[8:9]
	v_and_b32_e32 v143, 0xffff0000, v75
	s_waitcnt lgkmcnt(0)
	v_mul_f32_e32 v25, v68, v4
	v_mul_f32_e32 v50, v68, v40
	v_fmac_f32_e32 v25, v69, v5
	v_fmac_f32_e32 v50, v69, v41
	v_fmac_f32_e32 v25, v70, v6
	v_fmac_f32_e32 v50, v70, v42
	v_fmac_f32_e32 v25, v71, v7
	v_fmac_f32_e32 v50, v71, v43
	v_mul_f32_e32 v52, v24, v12
	ds_read_b128 v[40:43], v156 offset:7088
	v_add_f32_dpp v25, v25, v25 row_ror:8 row_mask:0xf bank_mask:0xf bound_ctrl:1
	v_mul_f32_e32 v53, v24, v13
	v_add_f32_dpp v50, v50, v50 row_ror:8 row_mask:0xf bank_mask:0xf bound_ctrl:1
	ds_read_b128 v[28:31], v156 offset:7040
	v_mul_f32_e32 v54, v24, v14
	ds_read_b128 v[32:35], v156 offset:7056
	v_add_f32_dpp v25, v25, v25 row_ror:4 row_mask:0xf bank_mask:0xf bound_ctrl:1
	v_mul_f32_e32 v55, v24, v15
	v_add_f32_dpp v50, v50, v50 row_ror:4 row_mask:0xf bank_mask:0xf bound_ctrl:1
	ds_read_b128 v[36:39], v156 offset:7072
	v_fma_f32 v56, v68, v20, v52
	ds_read_b128 v[44:47], v156 offset:7104
	v_add_f32_dpp v25, v25, v25 row_ror:2 row_mask:0xf bank_mask:0xf bound_ctrl:1
	v_fma_f32 v57, v69, v21, v53
	v_add_f32_dpp v50, v50, v50 row_ror:2 row_mask:0xf bank_mask:0xf bound_ctrl:1
	ds_read_u16_d16_hi v48, v157 offset:7040
	v_fma_f32 v58, v70, v22, v54
	ds_write_b128 v155, v[136:139] offset:0
	v_add_f32_dpp v25, v25, v25 row_ror:1 row_mask:0xf bank_mask:0xf bound_ctrl:1
	v_fma_f32 v59, v71, v23, v55
	v_add_f32_dpp v50, v50, v50 row_ror:1 row_mask:0xf bank_mask:0xf bound_ctrl:1
	ds_write_b128 v155, v[140:143] offset:80
	s_nop 0
	v_fma_f32 v68, -v25, v8, v56
	v_fma_f32 v69, -v25, v9, v57
	v_fma_f32 v70, -v25, v10, v58
	v_fma_f32 v71, -v25, v11, v59
	v_cndmask_b32_e64 v60, v60, v50, s[10:11]
	v_lshlrev_b32_e32 v136, 16, v76
	s_waitcnt lgkmcnt(0)
	v_mul_f32_e32 v49, v68, v28
	v_mul_f32_e32 v26, v68, v16
	v_fmac_f32_e32 v49, v69, v29
	v_fmac_f32_e32 v26, v69, v17
	v_fmac_f32_e32 v49, v70, v30
	v_fmac_f32_e32 v26, v70, v18
	v_fmac_f32_e32 v49, v71, v31
	v_fmac_f32_e32 v26, v71, v19
	v_mul_f32_e32 v52, v48, v36
	ds_read_b128 v[16:19], v156 offset:8496
	v_add_f32_dpp v49, v49, v49 row_ror:8 row_mask:0xf bank_mask:0xf bound_ctrl:1
	v_mul_f32_e32 v53, v48, v37
	v_add_f32_dpp v26, v26, v26 row_ror:8 row_mask:0xf bank_mask:0xf bound_ctrl:1
	ds_read_b128 v[4:7], v156 offset:8448
	v_mul_f32_e32 v54, v48, v38
	ds_read_b128 v[8:11], v156 offset:8464
	v_add_f32_dpp v49, v49, v49 row_ror:4 row_mask:0xf bank_mask:0xf bound_ctrl:1
	v_mul_f32_e32 v55, v48, v39
	v_add_f32_dpp v26, v26, v26 row_ror:4 row_mask:0xf bank_mask:0xf bound_ctrl:1
	ds_read_b128 v[12:15], v156 offset:8480
	v_fma_f32 v56, v68, v44, v52
	ds_read_b128 v[20:23], v156 offset:8512
	v_add_f32_dpp v49, v49, v49 row_ror:2 row_mask:0xf bank_mask:0xf bound_ctrl:1
	v_fma_f32 v57, v69, v45, v53
	v_add_f32_dpp v26, v26, v26 row_ror:2 row_mask:0xf bank_mask:0xf bound_ctrl:1
	ds_read_u16_d16_hi v24, v157 offset:8448
	v_fma_f32 v58, v70, v46, v54
	v_and_b32_e32 v137, 0xffff0000, v76
	v_add_f32_dpp v49, v49, v49 row_ror:1 row_mask:0xf bank_mask:0xf bound_ctrl:1
	v_fma_f32 v59, v71, v47, v55
	v_add_f32_dpp v26, v26, v26 row_ror:1 row_mask:0xf bank_mask:0xf bound_ctrl:1
	v_lshlrev_b32_e32 v138, 16, v77
	s_nop 0
	v_fma_f32 v68, -v49, v32, v56
	v_fma_f32 v69, -v49, v33, v57
	v_fma_f32 v70, -v49, v34, v58
	v_fma_f32 v71, -v49, v35, v59
	v_cndmask_b32_e64 v60, v60, v26, s[12:13]
	v_and_b32_e32 v139, 0xffff0000, v77
	s_waitcnt lgkmcnt(0)
	v_mul_f32_e32 v25, v68, v4
	v_mul_f32_e32 v50, v68, v40
	v_fmac_f32_e32 v25, v69, v5
	v_fmac_f32_e32 v50, v69, v41
	v_fmac_f32_e32 v25, v70, v6
	v_fmac_f32_e32 v50, v70, v42
	v_fmac_f32_e32 v25, v71, v7
	v_fmac_f32_e32 v50, v71, v43
	v_mul_f32_e32 v52, v24, v12
	ds_read_b128 v[40:43], v156 offset:9904
	v_add_f32_dpp v25, v25, v25 row_ror:8 row_mask:0xf bank_mask:0xf bound_ctrl:1
	v_mul_f32_e32 v53, v24, v13
	v_add_f32_dpp v50, v50, v50 row_ror:8 row_mask:0xf bank_mask:0xf bound_ctrl:1
	ds_read_b128 v[28:31], v156 offset:9856
	v_mul_f32_e32 v54, v24, v14
	ds_read_b128 v[32:35], v156 offset:9872
	v_add_f32_dpp v25, v25, v25 row_ror:4 row_mask:0xf bank_mask:0xf bound_ctrl:1
	v_mul_f32_e32 v55, v24, v15
	v_add_f32_dpp v50, v50, v50 row_ror:4 row_mask:0xf bank_mask:0xf bound_ctrl:1
	ds_read_b128 v[36:39], v156 offset:9888
	v_fma_f32 v56, v68, v20, v52
	ds_read_b128 v[44:47], v156 offset:9920
	v_add_f32_dpp v25, v25, v25 row_ror:2 row_mask:0xf bank_mask:0xf bound_ctrl:1
	v_fma_f32 v57, v69, v21, v53
	v_add_f32_dpp v50, v50, v50 row_ror:2 row_mask:0xf bank_mask:0xf bound_ctrl:1
	ds_read_u16_d16_hi v48, v157 offset:9856
	v_fma_f32 v58, v70, v22, v54
	v_lshlrev_b32_e32 v140, 16, v78
	v_add_f32_dpp v25, v25, v25 row_ror:1 row_mask:0xf bank_mask:0xf bound_ctrl:1
	v_fma_f32 v59, v71, v23, v55
	v_add_f32_dpp v50, v50, v50 row_ror:1 row_mask:0xf bank_mask:0xf bound_ctrl:1
	v_and_b32_e32 v141, 0xffff0000, v78
	s_nop 0
	v_fma_f32 v68, -v25, v8, v56
	v_fma_f32 v69, -v25, v9, v57
	v_fma_f32 v70, -v25, v10, v58
	v_fma_f32 v71, -v25, v11, v59
	v_cndmask_b32_e64 v60, v60, v50, s[14:15]
	v_lshlrev_b32_e32 v142, 16, v79
	s_waitcnt lgkmcnt(0)
	v_mul_f32_e32 v49, v68, v28
	v_mul_f32_e32 v26, v68, v16
	v_fmac_f32_e32 v49, v69, v29
	v_fmac_f32_e32 v26, v69, v17
	v_fmac_f32_e32 v49, v70, v30
	v_fmac_f32_e32 v26, v70, v18
	v_fmac_f32_e32 v49, v71, v31
	v_fmac_f32_e32 v26, v71, v19
	v_mul_f32_e32 v52, v48, v36
	ds_read_b128 v[16:19], v156 offset:11312
	v_add_f32_dpp v49, v49, v49 row_ror:8 row_mask:0xf bank_mask:0xf bound_ctrl:1
	v_mul_f32_e32 v53, v48, v37
	v_add_f32_dpp v26, v26, v26 row_ror:8 row_mask:0xf bank_mask:0xf bound_ctrl:1
	ds_read_b128 v[4:7], v156 offset:11264
	v_mul_f32_e32 v54, v48, v38
	ds_read_b128 v[8:11], v156 offset:11280
	v_add_f32_dpp v49, v49, v49 row_ror:4 row_mask:0xf bank_mask:0xf bound_ctrl:1
	v_mul_f32_e32 v55, v48, v39
	v_add_f32_dpp v26, v26, v26 row_ror:4 row_mask:0xf bank_mask:0xf bound_ctrl:1
	ds_read_b128 v[12:15], v156 offset:11296
	v_fma_f32 v56, v68, v44, v52
	ds_read_b128 v[20:23], v156 offset:11328
	v_add_f32_dpp v49, v49, v49 row_ror:2 row_mask:0xf bank_mask:0xf bound_ctrl:1
	v_fma_f32 v57, v69, v45, v53
	v_add_f32_dpp v26, v26, v26 row_ror:2 row_mask:0xf bank_mask:0xf bound_ctrl:1
	ds_read_u16_d16_hi v24, v157 offset:11264
	v_fma_f32 v58, v70, v46, v54
	v_and_b32_e32 v143, 0xffff0000, v79
	v_add_f32_dpp v49, v49, v49 row_ror:1 row_mask:0xf bank_mask:0xf bound_ctrl:1
	v_fma_f32 v59, v71, v47, v55
	v_add_f32_dpp v26, v26, v26 row_ror:1 row_mask:0xf bank_mask:0xf bound_ctrl:1
	ds_write_b128 v155, v[136:139] offset:11264
	s_nop 0
	v_fma_f32 v68, -v49, v32, v56
	v_fma_f32 v69, -v49, v33, v57
	v_fma_f32 v70, -v49, v34, v58
	v_fma_f32 v71, -v49, v35, v59
	v_cndmask_b32_e64 v60, v60, v26, s[16:17]
	ds_write_b128 v155, v[140:143] offset:11344
	s_waitcnt lgkmcnt(0)
	v_mul_f32_e32 v25, v68, v4
	v_mul_f32_e32 v50, v68, v40
	v_fmac_f32_e32 v25, v69, v5
	v_fmac_f32_e32 v50, v69, v41
	v_fmac_f32_e32 v25, v70, v6
	v_fmac_f32_e32 v50, v70, v42
	v_fmac_f32_e32 v25, v71, v7
	v_fmac_f32_e32 v50, v71, v43
	v_mul_f32_e32 v52, v24, v12
	ds_read_b128 v[40:43], v156 offset:12720
	v_add_f32_dpp v25, v25, v25 row_ror:8 row_mask:0xf bank_mask:0xf bound_ctrl:1
	v_mul_f32_e32 v53, v24, v13
	v_add_f32_dpp v50, v50, v50 row_ror:8 row_mask:0xf bank_mask:0xf bound_ctrl:1
	ds_read_b128 v[28:31], v156 offset:12672
	v_mul_f32_e32 v54, v24, v14
	ds_read_b128 v[32:35], v156 offset:12688
	v_add_f32_dpp v25, v25, v25 row_ror:4 row_mask:0xf bank_mask:0xf bound_ctrl:1
	v_mul_f32_e32 v55, v24, v15
	v_add_f32_dpp v50, v50, v50 row_ror:4 row_mask:0xf bank_mask:0xf bound_ctrl:1
	ds_read_b128 v[36:39], v156 offset:12704
	v_fma_f32 v56, v68, v20, v52
	ds_read_b128 v[44:47], v156 offset:12736
	v_add_f32_dpp v25, v25, v25 row_ror:2 row_mask:0xf bank_mask:0xf bound_ctrl:1
	v_fma_f32 v57, v69, v21, v53
	v_add_f32_dpp v50, v50, v50 row_ror:2 row_mask:0xf bank_mask:0xf bound_ctrl:1
	ds_read_u16_d16_hi v48, v157 offset:12672
	v_fma_f32 v58, v70, v22, v54
	ds_write_b128 v165, v[80:83]
	v_add_f32_dpp v25, v25, v25 row_ror:1 row_mask:0xf bank_mask:0xf bound_ctrl:1
	v_fma_f32 v59, v71, v23, v55
	v_add_f32_dpp v50, v50, v50 row_ror:1 row_mask:0xf bank_mask:0xf bound_ctrl:1
	ds_write_b128 v166, v[84:87]
	s_nop 0
	v_fma_f32 v68, -v25, v8, v56
	v_fma_f32 v69, -v25, v9, v57
	v_fma_f32 v70, -v25, v10, v58
	v_fma_f32 v71, -v25, v11, v59
	v_cndmask_b32_e64 v60, v60, v50, s[18:19]
	global_load_dwordx4 v[72:75], v[144:145], off
	s_waitcnt lgkmcnt(0)
	v_mul_f32_e32 v49, v68, v28
	v_mul_f32_e32 v26, v68, v16
	v_fmac_f32_e32 v49, v69, v29
	v_fmac_f32_e32 v26, v69, v17
	v_fmac_f32_e32 v49, v70, v30
	v_fmac_f32_e32 v26, v70, v18
	v_fmac_f32_e32 v49, v71, v31
	v_fmac_f32_e32 v26, v71, v19
	v_mul_f32_e32 v52, v48, v36
	ds_read_b128 v[16:19], v156 offset:14128
	v_add_f32_dpp v49, v49, v49 row_ror:8 row_mask:0xf bank_mask:0xf bound_ctrl:1
	v_mul_f32_e32 v53, v48, v37
	v_add_f32_dpp v26, v26, v26 row_ror:8 row_mask:0xf bank_mask:0xf bound_ctrl:1
	ds_read_b128 v[4:7], v156 offset:14080
	v_mul_f32_e32 v54, v48, v38
	ds_read_b128 v[8:11], v156 offset:14096
	v_add_f32_dpp v49, v49, v49 row_ror:4 row_mask:0xf bank_mask:0xf bound_ctrl:1
	v_mul_f32_e32 v55, v48, v39
	v_add_f32_dpp v26, v26, v26 row_ror:4 row_mask:0xf bank_mask:0xf bound_ctrl:1
	ds_read_b128 v[12:15], v156 offset:14112
	v_fma_f32 v56, v68, v44, v52
	ds_read_b128 v[20:23], v156 offset:14144
	v_add_f32_dpp v49, v49, v49 row_ror:2 row_mask:0xf bank_mask:0xf bound_ctrl:1
	v_fma_f32 v57, v69, v45, v53
	v_add_f32_dpp v26, v26, v26 row_ror:2 row_mask:0xf bank_mask:0xf bound_ctrl:1
	ds_read_u16_d16_hi v24, v157 offset:14080
	v_fma_f32 v58, v70, v46, v54
	global_load_dwordx4 v[76:79], v[146:147], off
	v_add_f32_dpp v49, v49, v49 row_ror:1 row_mask:0xf bank_mask:0xf bound_ctrl:1
	v_fma_f32 v59, v71, v47, v55
	v_add_f32_dpp v26, v26, v26 row_ror:1 row_mask:0xf bank_mask:0xf bound_ctrl:1
	global_load_dwordx4 v[80:83], v[148:149], off
	s_nop 0
	v_fma_f32 v68, -v49, v32, v56
	v_fma_f32 v69, -v49, v33, v57
	v_fma_f32 v70, -v49, v34, v58
	v_fma_f32 v71, -v49, v35, v59
	v_cndmask_b32_e64 v60, v60, v26, s[20:21]
	global_load_dwordx4 v[84:87], v[150:151], off
	s_waitcnt lgkmcnt(0)
	v_mul_f32_e32 v25, v68, v4
	v_mul_f32_e32 v50, v68, v40
	v_fmac_f32_e32 v25, v69, v5
	v_fmac_f32_e32 v50, v69, v41
	v_fmac_f32_e32 v25, v70, v6
	v_fmac_f32_e32 v50, v70, v42
	v_fmac_f32_e32 v25, v71, v7
	v_fmac_f32_e32 v50, v71, v43
	v_mul_f32_e32 v52, v24, v12
	ds_read_b128 v[40:43], v156 offset:15536
	v_add_f32_dpp v25, v25, v25 row_ror:8 row_mask:0xf bank_mask:0xf bound_ctrl:1
	v_mul_f32_e32 v53, v24, v13
	v_add_f32_dpp v50, v50, v50 row_ror:8 row_mask:0xf bank_mask:0xf bound_ctrl:1
	ds_read_b128 v[28:31], v156 offset:15488
	v_mul_f32_e32 v54, v24, v14
	ds_read_b128 v[32:35], v156 offset:15504
	v_add_f32_dpp v25, v25, v25 row_ror:4 row_mask:0xf bank_mask:0xf bound_ctrl:1
	v_mul_f32_e32 v55, v24, v15
	v_add_f32_dpp v50, v50, v50 row_ror:4 row_mask:0xf bank_mask:0xf bound_ctrl:1
	ds_read_b128 v[36:39], v156 offset:15520
	v_fma_f32 v56, v68, v20, v52
	ds_read_b128 v[44:47], v156 offset:15552
	v_add_f32_dpp v25, v25, v25 row_ror:2 row_mask:0xf bank_mask:0xf bound_ctrl:1
	v_fma_f32 v57, v69, v21, v53
	v_add_f32_dpp v50, v50, v50 row_ror:2 row_mask:0xf bank_mask:0xf bound_ctrl:1
	ds_read_u16_d16_hi v48, v157 offset:15488
	v_fma_f32 v58, v70, v22, v54
	v_lshl_add_u64 v[144:145], v[144:145], 0, v[152:153]
	v_add_f32_dpp v25, v25, v25 row_ror:1 row_mask:0xf bank_mask:0xf bound_ctrl:1
	v_fma_f32 v59, v71, v23, v55
	v_add_f32_dpp v50, v50, v50 row_ror:1 row_mask:0xf bank_mask:0xf bound_ctrl:1
	v_lshl_add_u64 v[146:147], v[146:147], 0, v[152:153]
	s_nop 0
	v_fma_f32 v68, -v25, v8, v56
	v_fma_f32 v69, -v25, v9, v57
	v_fma_f32 v70, -v25, v10, v58
	v_fma_f32 v71, -v25, v11, v59
	v_cndmask_b32_e64 v60, v60, v50, s[22:23]
	v_lshl_add_u64 v[148:149], v[148:149], 0, v[62:63]
	s_waitcnt lgkmcnt(0)
	v_mul_f32_e32 v49, v68, v28
	v_mul_f32_e32 v26, v68, v16
	v_fmac_f32_e32 v49, v69, v29
	v_fmac_f32_e32 v26, v69, v17
	v_fmac_f32_e32 v49, v70, v30
	v_fmac_f32_e32 v26, v70, v18
	v_fmac_f32_e32 v49, v71, v31
	v_fmac_f32_e32 v26, v71, v19
	v_mul_f32_e32 v52, v48, v36
	ds_read_b128 v[16:19], v156 offset:16944
	v_add_f32_dpp v49, v49, v49 row_ror:8 row_mask:0xf bank_mask:0xf bound_ctrl:1
	v_mul_f32_e32 v53, v48, v37
	v_add_f32_dpp v26, v26, v26 row_ror:8 row_mask:0xf bank_mask:0xf bound_ctrl:1
	ds_read_b128 v[4:7], v156 offset:16896
	v_mul_f32_e32 v54, v48, v38
	ds_read_b128 v[8:11], v156 offset:16912
	v_add_f32_dpp v49, v49, v49 row_ror:4 row_mask:0xf bank_mask:0xf bound_ctrl:1
	v_mul_f32_e32 v55, v48, v39
	v_add_f32_dpp v26, v26, v26 row_ror:4 row_mask:0xf bank_mask:0xf bound_ctrl:1
	ds_read_b128 v[12:15], v156 offset:16928
	v_fma_f32 v56, v68, v44, v52
	ds_read_b128 v[20:23], v156 offset:16960
	v_add_f32_dpp v49, v49, v49 row_ror:2 row_mask:0xf bank_mask:0xf bound_ctrl:1
	v_fma_f32 v57, v69, v45, v53
	v_add_f32_dpp v26, v26, v26 row_ror:2 row_mask:0xf bank_mask:0xf bound_ctrl:1
	ds_read_u16_d16_hi v24, v157 offset:16896
	v_fma_f32 v58, v70, v46, v54
	v_lshl_add_u64 v[150:151], v[150:151], 0, v[64:65]
	v_add_f32_dpp v49, v49, v49 row_ror:1 row_mask:0xf bank_mask:0xf bound_ctrl:1
	v_fma_f32 v59, v71, v47, v55
	v_add_f32_dpp v26, v26, v26 row_ror:1 row_mask:0xf bank_mask:0xf bound_ctrl:1
	v_add_u32_e32 v158, s43, v162
	s_nop 0
	v_fma_f32 v68, -v49, v32, v56
	v_fma_f32 v69, -v49, v33, v57
	v_fma_f32 v70, -v49, v34, v58
	v_fma_f32 v71, -v49, v35, v59
	v_cndmask_b32_e64 v60, v60, v26, s[24:25]
	v_add_u32_e32 v159, s43, v163
	s_waitcnt lgkmcnt(0)
; DEVI void rw_chain_task(const Params& p, int l, int seq, int head, int quarter, char* smem) {
;     ...
;       lds_barrier();
;       RW_STORE(R0, B0);
;       RW_LOAD(R0, c + 8);
	v_mul_f32_e32 v25, v68, v4
	v_mul_f32_e32 v50, v68, v40
	v_fmac_f32_e32 v25, v69, v5
	v_fmac_f32_e32 v50, v69, v41
	v_fmac_f32_e32 v25, v70, v6
	v_fmac_f32_e32 v50, v70, v42
	v_fmac_f32_e32 v25, v71, v7
	v_fmac_f32_e32 v50, v71, v43
	v_mul_f32_e32 v52, v24, v12
	ds_read_b128 v[40:43], v156 offset:18352
	v_add_f32_dpp v25, v25, v25 row_ror:8 row_mask:0xf bank_mask:0xf bound_ctrl:1
	v_mul_f32_e32 v53, v24, v13
	v_add_f32_dpp v50, v50, v50 row_ror:8 row_mask:0xf bank_mask:0xf bound_ctrl:1
	ds_read_b128 v[28:31], v156 offset:18304
	v_mul_f32_e32 v54, v24, v14
	ds_read_b128 v[32:35], v156 offset:18320
	v_add_f32_dpp v25, v25, v25 row_ror:4 row_mask:0xf bank_mask:0xf bound_ctrl:1
	v_mul_f32_e32 v55, v24, v15
	v_add_f32_dpp v50, v50, v50 row_ror:4 row_mask:0xf bank_mask:0xf bound_ctrl:1
	ds_read_b128 v[36:39], v156 offset:18336
	v_fma_f32 v56, v68, v20, v52
	ds_read_b128 v[44:47], v156 offset:18368
	v_add_f32_dpp v25, v25, v25 row_ror:2 row_mask:0xf bank_mask:0xf bound_ctrl:1
	v_fma_f32 v57, v69, v21, v53
	v_add_f32_dpp v50, v50, v50 row_ror:2 row_mask:0xf bank_mask:0xf bound_ctrl:1
	ds_read_u16_d16_hi v48, v157 offset:18304
	v_fma_f32 v58, v70, v22, v54
	v_add_f32_dpp v25, v25, v25 row_ror:1 row_mask:0xf bank_mask:0xf bound_ctrl:1
	v_fma_f32 v59, v71, v23, v55
	v_add_f32_dpp v50, v50, v50 row_ror:1 row_mask:0xf bank_mask:0xf bound_ctrl:1
	s_nop 0
	v_fma_f32 v68, -v25, v8, v56
	v_fma_f32 v69, -v25, v9, v57
	v_fma_f32 v70, -v25, v10, v58
	v_fma_f32 v71, -v25, v11, v59
	v_cndmask_b32_e64 v60, v60, v50, s[26:27]
	s_waitcnt lgkmcnt(0)
	v_mul_f32_e32 v49, v68, v28
	v_mul_f32_e32 v26, v68, v16
	v_fmac_f32_e32 v49, v69, v29
	v_fmac_f32_e32 v26, v69, v17
	v_fmac_f32_e32 v49, v70, v30
	v_fmac_f32_e32 v26, v70, v18
	v_fmac_f32_e32 v49, v71, v31
	v_fmac_f32_e32 v26, v71, v19
	v_mul_f32_e32 v52, v48, v36
	ds_read_b128 v[16:19], v156 offset:19760
	v_add_f32_dpp v49, v49, v49 row_ror:8 row_mask:0xf bank_mask:0xf bound_ctrl:1
	v_mul_f32_e32 v53, v48, v37
	v_add_f32_dpp v26, v26, v26 row_ror:8 row_mask:0xf bank_mask:0xf bound_ctrl:1
	ds_read_b128 v[4:7], v156 offset:19712
	v_mul_f32_e32 v54, v48, v38
	ds_read_b128 v[8:11], v156 offset:19728
	v_add_f32_dpp v49, v49, v49 row_ror:4 row_mask:0xf bank_mask:0xf bound_ctrl:1
	v_mul_f32_e32 v55, v48, v39
	v_add_f32_dpp v26, v26, v26 row_ror:4 row_mask:0xf bank_mask:0xf bound_ctrl:1
	ds_read_b128 v[12:15], v156 offset:19744
	v_fma_f32 v56, v68, v44, v52
	ds_read_b128 v[20:23], v156 offset:19776
	v_add_f32_dpp v49, v49, v49 row_ror:2 row_mask:0xf bank_mask:0xf bound_ctrl:1
	v_fma_f32 v57, v69, v45, v53
	v_add_f32_dpp v26, v26, v26 row_ror:2 row_mask:0xf bank_mask:0xf bound_ctrl:1
	ds_read_u16_d16_hi v24, v157 offset:19712
	v_fma_f32 v58, v70, v46, v54
	v_add_f32_dpp v49, v49, v49 row_ror:1 row_mask:0xf bank_mask:0xf bound_ctrl:1
	v_fma_f32 v59, v71, v47, v55
	v_add_f32_dpp v26, v26, v26 row_ror:1 row_mask:0xf bank_mask:0xf bound_ctrl:1
	s_nop 0
	v_fma_f32 v68, -v49, v32, v56
	v_fma_f32 v69, -v49, v33, v57
	v_fma_f32 v70, -v49, v34, v58
	v_fma_f32 v71, -v49, v35, v59
	v_cndmask_b32_e64 v60, v60, v26, s[28:29]
	s_waitcnt lgkmcnt(0)
	v_mul_f32_e32 v25, v68, v4
	v_mul_f32_e32 v50, v68, v40
	v_fmac_f32_e32 v25, v69, v5
	v_fmac_f32_e32 v50, v69, v41
	v_fmac_f32_e32 v25, v70, v6
	v_fmac_f32_e32 v50, v70, v42
	v_fmac_f32_e32 v25, v71, v7
	v_fmac_f32_e32 v50, v71, v43
	v_mul_f32_e32 v52, v24, v12
	ds_read_b128 v[40:43], v156 offset:21168
	v_add_f32_dpp v25, v25, v25 row_ror:8 row_mask:0xf bank_mask:0xf bound_ctrl:1
	v_mul_f32_e32 v53, v24, v13
	v_add_f32_dpp v50, v50, v50 row_ror:8 row_mask:0xf bank_mask:0xf bound_ctrl:1
	ds_read_b128 v[28:31], v156 offset:21120
	v_mul_f32_e32 v54, v24, v14
	ds_read_b128 v[32:35], v156 offset:21136
	v_add_f32_dpp v25, v25, v25 row_ror:4 row_mask:0xf bank_mask:0xf bound_ctrl:1
	v_mul_f32_e32 v55, v24, v15
	v_add_f32_dpp v50, v50, v50 row_ror:4 row_mask:0xf bank_mask:0xf bound_ctrl:1
	ds_read_b128 v[36:39], v156 offset:21152
	v_fma_f32 v56, v68, v20, v52
	ds_read_b128 v[44:47], v156 offset:21184
	v_add_f32_dpp v25, v25, v25 row_ror:2 row_mask:0xf bank_mask:0xf bound_ctrl:1
	v_fma_f32 v57, v69, v21, v53
	v_add_f32_dpp v50, v50, v50 row_ror:2 row_mask:0xf bank_mask:0xf bound_ctrl:1
	ds_read_u16_d16_hi v48, v157 offset:21120
	v_fma_f32 v58, v70, v22, v54
	v_add_f32_dpp v25, v25, v25 row_ror:1 row_mask:0xf bank_mask:0xf bound_ctrl:1
	v_fma_f32 v59, v71, v23, v55
	v_add_f32_dpp v50, v50, v50 row_ror:1 row_mask:0xf bank_mask:0xf bound_ctrl:1
	s_nop 0
	v_fma_f32 v68, -v25, v8, v56
	v_fma_f32 v69, -v25, v9, v57
	v_fma_f32 v70, -v25, v10, v58
	v_fma_f32 v71, -v25, v11, v59
	v_cndmask_b32_e64 v60, v60, v50, s[30:31]
	s_waitcnt lgkmcnt(0)
	v_mul_f32_e32 v49, v68, v28
	v_mul_f32_e32 v26, v68, v16
	v_fmac_f32_e32 v49, v69, v29
	v_fmac_f32_e32 v26, v69, v17
	v_fmac_f32_e32 v49, v70, v30
	v_fmac_f32_e32 v26, v70, v18
	v_fmac_f32_e32 v49, v71, v31
	v_fmac_f32_e32 v26, v71, v19
	v_mul_f32_e32 v52, v48, v36
	ds_read_b128 v[16:19], v158 offset:48
	v_add_f32_dpp v49, v49, v49 row_ror:8 row_mask:0xf bank_mask:0xf bound_ctrl:1
	v_mul_f32_e32 v53, v48, v37
	v_add_f32_dpp v26, v26, v26 row_ror:8 row_mask:0xf bank_mask:0xf bound_ctrl:1
	ds_read_b128 v[4:7], v158 offset:0
	v_mul_f32_e32 v54, v48, v38
	ds_read_b128 v[8:11], v158 offset:16
	v_add_f32_dpp v49, v49, v49 row_ror:4 row_mask:0xf bank_mask:0xf bound_ctrl:1
	v_mul_f32_e32 v55, v48, v39
	v_add_f32_dpp v26, v26, v26 row_ror:4 row_mask:0xf bank_mask:0xf bound_ctrl:1
	ds_read_b128 v[12:15], v158 offset:32
	v_fma_f32 v56, v68, v44, v52
	ds_read_b128 v[20:23], v158 offset:64
	v_add_f32_dpp v49, v49, v49 row_ror:2 row_mask:0xf bank_mask:0xf bound_ctrl:1
	v_fma_f32 v57, v69, v45, v53
	v_add_f32_dpp v26, v26, v26 row_ror:2 row_mask:0xf bank_mask:0xf bound_ctrl:1
	ds_read_u16_d16_hi v24, v159 offset:0
	v_fma_f32 v58, v70, v46, v54
	v_add_f32_dpp v49, v49, v49 row_ror:1 row_mask:0xf bank_mask:0xf bound_ctrl:1
	v_fma_f32 v59, v71, v47, v55
	v_add_f32_dpp v26, v26, v26 row_ror:1 row_mask:0xf bank_mask:0xf bound_ctrl:1
	s_nop 0
	v_fma_f32 v68, -v49, v32, v56
	v_fma_f32 v69, -v49, v33, v57
	v_fma_f32 v70, -v49, v34, v58
	v_fma_f32 v71, -v49, v35, v59
	v_cndmask_b32_e64 v60, v60, v26, s[34:35]
	s_waitcnt lgkmcnt(0)
	s_barrier
; DEVI void rw_chain_task(const Params& p, int l, int seq, int head, int quarter, char* smem) {
;     ...
;       lds_barrier();
;       RW_STORE(R0, B0);
;       RW_LOAD(R0, c + 8);
;       RW_COMPUTE(B1, c + 3);
	s_mov_b32 vcc_lo, s42
	s_mov_b32 s42, s43
	s_mov_b32 s43, s45
	s_mov_b32 s45, vcc_lo
	v_add_u32_e32 v156, s42, v162
	v_add_u32_e32 v157, s42, v163
	v_add_u32_e32 v155, s45, v164
	v_add_u32_e32 v165, s45, v167
	v_add_u32_e32 v166, s45, v168
	s_waitcnt lgkmcnt(0)
	v_mul_f32_e32 v25, v68, v4
	v_mul_f32_e32 v50, v68, v40
	v_fmac_f32_e32 v25, v69, v5
	v_fmac_f32_e32 v50, v69, v41
	v_fmac_f32_e32 v25, v70, v6
	v_fmac_f32_e32 v50, v70, v42
	v_fmac_f32_e32 v25, v71, v7
	v_fmac_f32_e32 v50, v71, v43
	v_mul_f32_e32 v52, v24, v12
	ds_read_b128 v[40:43], v156 offset:1456
	v_add_f32_dpp v25, v25, v25 row_ror:8 row_mask:0xf bank_mask:0xf bound_ctrl:1
	v_mul_f32_e32 v53, v24, v13
	v_add_f32_dpp v50, v50, v50 row_ror:8 row_mask:0xf bank_mask:0xf bound_ctrl:1
	ds_read_b128 v[28:31], v156 offset:1408
	v_mul_f32_e32 v54, v24, v14
	ds_read_b128 v[32:35], v156 offset:1424
	v_add_f32_dpp v25, v25, v25 row_ror:4 row_mask:0xf bank_mask:0xf bound_ctrl:1
	v_mul_f32_e32 v55, v24, v15
	v_add_f32_dpp v50, v50, v50 row_ror:4 row_mask:0xf bank_mask:0xf bound_ctrl:1
	ds_read_b128 v[36:39], v156 offset:1440
	v_fma_f32 v56, v68, v20, v52
	ds_read_b128 v[44:47], v156 offset:1472
	v_add_f32_dpp v25, v25, v25 row_ror:2 row_mask:0xf bank_mask:0xf bound_ctrl:1
	v_fma_f32 v57, v69, v21, v53
	v_add_f32_dpp v50, v50, v50 row_ror:2 row_mask:0xf bank_mask:0xf bound_ctrl:1
	ds_read_u16_d16_hi v48, v157 offset:1408
	v_fma_f32 v58, v70, v22, v54
	v_add_f32_dpp v25, v25, v25 row_ror:1 row_mask:0xf bank_mask:0xf bound_ctrl:1
	v_fma_f32 v59, v71, v23, v55
	v_add_f32_dpp v50, v50, v50 row_ror:1 row_mask:0xf bank_mask:0xf bound_ctrl:1
	s_nop 0
	v_fma_f32 v68, -v25, v8, v56
	v_fma_f32 v69, -v25, v9, v57
	v_fma_f32 v70, -v25, v10, v58
	v_fma_f32 v71, -v25, v11, v59
	v_cndmask_b32_e64 v60, v60, v50, s[36:37]
	v_bfe_u32 v61, v60, 16, 1
	v_add3_u32 v61, v60, v61, s33
	global_store_short_d16_hi v[160:161], v61, off
	v_lshl_add_u64 v[160:161], v[160:161], 0, s[46:47]
	s_waitcnt lgkmcnt(0)
	v_mul_f32_e32 v49, v68, v28
	v_mul_f32_e32 v26, v68, v16
	v_fmac_f32_e32 v49, v69, v29
	v_fmac_f32_e32 v26, v69, v17
	v_fmac_f32_e32 v49, v70, v30
	v_fmac_f32_e32 v26, v70, v18
	v_fmac_f32_e32 v49, v71, v31
	v_fmac_f32_e32 v26, v71, v19
	v_mul_f32_e32 v52, v48, v36
	ds_read_b128 v[16:19], v156 offset:2864
	v_add_f32_dpp v49, v49, v49 row_ror:8 row_mask:0xf bank_mask:0xf bound_ctrl:1
	v_mul_f32_e32 v53, v48, v37
	v_add_f32_dpp v26, v26, v26 row_ror:8 row_mask:0xf bank_mask:0xf bound_ctrl:1
	ds_read_b128 v[4:7], v156 offset:2816
	v_mul_f32_e32 v54, v48, v38
	ds_read_b128 v[8:11], v156 offset:2832
	v_add_f32_dpp v49, v49, v49 row_ror:4 row_mask:0xf bank_mask:0xf bound_ctrl:1
	v_mul_f32_e32 v55, v48, v39
	v_add_f32_dpp v26, v26, v26 row_ror:4 row_mask:0xf bank_mask:0xf bound_ctrl:1
	ds_read_b128 v[12:15], v156 offset:2848
	v_fma_f32 v56, v68, v44, v52
	ds_read_b128 v[20:23], v156 offset:2880
	v_add_f32_dpp v49, v49, v49 row_ror:2 row_mask:0xf bank_mask:0xf bound_ctrl:1
	v_fma_f32 v57, v69, v45, v53
	v_add_f32_dpp v26, v26, v26 row_ror:2 row_mask:0xf bank_mask:0xf bound_ctrl:1
	ds_read_u16_d16_hi v24, v157 offset:2816
	v_fma_f32 v58, v70, v46, v54
	s_waitcnt vmcnt(12)
	v_add_f32_dpp v49, v49, v49 row_ror:1 row_mask:0xf bank_mask:0xf bound_ctrl:1
	v_fma_f32 v59, v71, v47, v55
	v_add_f32_dpp v26, v26, v26 row_ror:1 row_mask:0xf bank_mask:0xf bound_ctrl:1
	v_lshlrev_b32_e32 v136, 16, v88
	s_nop 0
	v_fma_f32 v68, -v49, v32, v56
	v_fma_f32 v69, -v49, v33, v57
	v_fma_f32 v70, -v49, v34, v58
	v_fma_f32 v71, -v49, v35, v59
	v_cndmask_b32_e64 v60, v60, v26, s[4:5]
	v_and_b32_e32 v137, 0xffff0000, v88
	s_waitcnt lgkmcnt(0)
	v_mul_f32_e32 v25, v68, v4
	v_mul_f32_e32 v50, v68, v40
	v_fmac_f32_e32 v25, v69, v5
	v_fmac_f32_e32 v50, v69, v41
	v_fmac_f32_e32 v25, v70, v6
	v_fmac_f32_e32 v50, v70, v42
	v_fmac_f32_e32 v25, v71, v7
	v_fmac_f32_e32 v50, v71, v43
	v_mul_f32_e32 v52, v24, v12
	ds_read_b128 v[40:43], v156 offset:4272
	v_add_f32_dpp v25, v25, v25 row_ror:8 row_mask:0xf bank_mask:0xf bound_ctrl:1
	v_mul_f32_e32 v53, v24, v13
	v_add_f32_dpp v50, v50, v50 row_ror:8 row_mask:0xf bank_mask:0xf bound_ctrl:1
	ds_read_b128 v[28:31], v156 offset:4224
	v_mul_f32_e32 v54, v24, v14
	ds_read_b128 v[32:35], v156 offset:4240
	v_add_f32_dpp v25, v25, v25 row_ror:4 row_mask:0xf bank_mask:0xf bound_ctrl:1
	v_mul_f32_e32 v55, v24, v15
	v_add_f32_dpp v50, v50, v50 row_ror:4 row_mask:0xf bank_mask:0xf bound_ctrl:1
	ds_read_b128 v[36:39], v156 offset:4256
	v_fma_f32 v56, v68, v20, v52
	ds_read_b128 v[44:47], v156 offset:4288
	v_add_f32_dpp v25, v25, v25 row_ror:2 row_mask:0xf bank_mask:0xf bound_ctrl:1
	v_fma_f32 v57, v69, v21, v53
	v_add_f32_dpp v50, v50, v50 row_ror:2 row_mask:0xf bank_mask:0xf bound_ctrl:1
	ds_read_u16_d16_hi v48, v157 offset:4224
	v_fma_f32 v58, v70, v22, v54
	v_lshlrev_b32_e32 v138, 16, v89
	v_add_f32_dpp v25, v25, v25 row_ror:1 row_mask:0xf bank_mask:0xf bound_ctrl:1
	v_fma_f32 v59, v71, v23, v55
	v_add_f32_dpp v50, v50, v50 row_ror:1 row_mask:0xf bank_mask:0xf bound_ctrl:1
	v_and_b32_e32 v139, 0xffff0000, v89
	s_nop 0
	v_fma_f32 v68, -v25, v8, v56
	v_fma_f32 v69, -v25, v9, v57
	v_fma_f32 v70, -v25, v10, v58
	v_fma_f32 v71, -v25, v11, v59
	v_cndmask_b32_e64 v60, v60, v50, s[6:7]
	v_lshlrev_b32_e32 v140, 16, v90
	s_waitcnt lgkmcnt(0)
	v_mul_f32_e32 v49, v68, v28
	v_mul_f32_e32 v26, v68, v16
	v_fmac_f32_e32 v49, v69, v29
	v_fmac_f32_e32 v26, v69, v17
	v_fmac_f32_e32 v49, v70, v30
	v_fmac_f32_e32 v26, v70, v18
	v_fmac_f32_e32 v49, v71, v31
	v_fmac_f32_e32 v26, v71, v19
	v_mul_f32_e32 v52, v48, v36
	ds_read_b128 v[16:19], v156 offset:5680
	v_add_f32_dpp v49, v49, v49 row_ror:8 row_mask:0xf bank_mask:0xf bound_ctrl:1
	v_mul_f32_e32 v53, v48, v37
	v_add_f32_dpp v26, v26, v26 row_ror:8 row_mask:0xf bank_mask:0xf bound_ctrl:1
	ds_read_b128 v[4:7], v156 offset:5632
	v_mul_f32_e32 v54, v48, v38
	ds_read_b128 v[8:11], v156 offset:5648
	v_add_f32_dpp v49, v49, v49 row_ror:4 row_mask:0xf bank_mask:0xf bound_ctrl:1
	v_mul_f32_e32 v55, v48, v39
	v_add_f32_dpp v26, v26, v26 row_ror:4 row_mask:0xf bank_mask:0xf bound_ctrl:1
	ds_read_b128 v[12:15], v156 offset:5664
	v_fma_f32 v56, v68, v44, v52
	ds_read_b128 v[20:23], v156 offset:5696
	v_add_f32_dpp v49, v49, v49 row_ror:2 row_mask:0xf bank_mask:0xf bound_ctrl:1
	v_fma_f32 v57, v69, v45, v53
	v_add_f32_dpp v26, v26, v26 row_ror:2 row_mask:0xf bank_mask:0xf bound_ctrl:1
	ds_read_u16_d16_hi v24, v157 offset:5632
	v_fma_f32 v58, v70, v46, v54
	v_and_b32_e32 v141, 0xffff0000, v90
	v_add_f32_dpp v49, v49, v49 row_ror:1 row_mask:0xf bank_mask:0xf bound_ctrl:1
	v_fma_f32 v59, v71, v47, v55
	v_add_f32_dpp v26, v26, v26 row_ror:1 row_mask:0xf bank_mask:0xf bound_ctrl:1
	v_lshlrev_b32_e32 v142, 16, v91
	s_nop 0
	v_fma_f32 v68, -v49, v32, v56
	v_fma_f32 v69, -v49, v33, v57
	v_fma_f32 v70, -v49, v34, v58
	v_fma_f32 v71, -v49, v35, v59
	v_cndmask_b32_e64 v60, v60, v26, s[8:9]
	v_and_b32_e32 v143, 0xffff0000, v91
	s_waitcnt lgkmcnt(0)
	v_mul_f32_e32 v25, v68, v4
	v_mul_f32_e32 v50, v68, v40
	v_fmac_f32_e32 v25, v69, v5
	v_fmac_f32_e32 v50, v69, v41
	v_fmac_f32_e32 v25, v70, v6
	v_fmac_f32_e32 v50, v70, v42
	v_fmac_f32_e32 v25, v71, v7
	v_fmac_f32_e32 v50, v71, v43
	v_mul_f32_e32 v52, v24, v12
	ds_read_b128 v[40:43], v156 offset:7088
	v_add_f32_dpp v25, v25, v25 row_ror:8 row_mask:0xf bank_mask:0xf bound_ctrl:1
	v_mul_f32_e32 v53, v24, v13
	v_add_f32_dpp v50, v50, v50 row_ror:8 row_mask:0xf bank_mask:0xf bound_ctrl:1
	ds_read_b128 v[28:31], v156 offset:7040
	v_mul_f32_e32 v54, v24, v14
	ds_read_b128 v[32:35], v156 offset:7056
	v_add_f32_dpp v25, v25, v25 row_ror:4 row_mask:0xf bank_mask:0xf bound_ctrl:1
	v_mul_f32_e32 v55, v24, v15
	v_add_f32_dpp v50, v50, v50 row_ror:4 row_mask:0xf bank_mask:0xf bound_ctrl:1
	ds_read_b128 v[36:39], v156 offset:7072
	v_fma_f32 v56, v68, v20, v52
	ds_read_b128 v[44:47], v156 offset:7104
	v_add_f32_dpp v25, v25, v25 row_ror:2 row_mask:0xf bank_mask:0xf bound_ctrl:1
	v_fma_f32 v57, v69, v21, v53
	v_add_f32_dpp v50, v50, v50 row_ror:2 row_mask:0xf bank_mask:0xf bound_ctrl:1
	ds_read_u16_d16_hi v48, v157 offset:7040
	v_fma_f32 v58, v70, v22, v54
	ds_write_b128 v155, v[136:139] offset:0
	v_add_f32_dpp v25, v25, v25 row_ror:1 row_mask:0xf bank_mask:0xf bound_ctrl:1
	v_fma_f32 v59, v71, v23, v55
	v_add_f32_dpp v50, v50, v50 row_ror:1 row_mask:0xf bank_mask:0xf bound_ctrl:1
	ds_write_b128 v155, v[140:143] offset:80
	s_nop 0
	v_fma_f32 v68, -v25, v8, v56
	v_fma_f32 v69, -v25, v9, v57
	v_fma_f32 v70, -v25, v10, v58
	v_fma_f32 v71, -v25, v11, v59
	v_cndmask_b32_e64 v60, v60, v50, s[10:11]
	v_lshlrev_b32_e32 v136, 16, v92
	s_waitcnt lgkmcnt(0)
	v_mul_f32_e32 v49, v68, v28
	v_mul_f32_e32 v26, v68, v16
	v_fmac_f32_e32 v49, v69, v29
	v_fmac_f32_e32 v26, v69, v17
	v_fmac_f32_e32 v49, v70, v30
	v_fmac_f32_e32 v26, v70, v18
	v_fmac_f32_e32 v49, v71, v31
	v_fmac_f32_e32 v26, v71, v19
	v_mul_f32_e32 v52, v48, v36
	ds_read_b128 v[16:19], v156 offset:8496
	v_add_f32_dpp v49, v49, v49 row_ror:8 row_mask:0xf bank_mask:0xf bound_ctrl:1
	v_mul_f32_e32 v53, v48, v37
	v_add_f32_dpp v26, v26, v26 row_ror:8 row_mask:0xf bank_mask:0xf bound_ctrl:1
	ds_read_b128 v[4:7], v156 offset:8448
	v_mul_f32_e32 v54, v48, v38
	ds_read_b128 v[8:11], v156 offset:8464
	v_add_f32_dpp v49, v49, v49 row_ror:4 row_mask:0xf bank_mask:0xf bound_ctrl:1
	v_mul_f32_e32 v55, v48, v39
	v_add_f32_dpp v26, v26, v26 row_ror:4 row_mask:0xf bank_mask:0xf bound_ctrl:1
	ds_read_b128 v[12:15], v156 offset:8480
	v_fma_f32 v56, v68, v44, v52
	ds_read_b128 v[20:23], v156 offset:8512
	v_add_f32_dpp v49, v49, v49 row_ror:2 row_mask:0xf bank_mask:0xf bound_ctrl:1
	v_fma_f32 v57, v69, v45, v53
	v_add_f32_dpp v26, v26, v26 row_ror:2 row_mask:0xf bank_mask:0xf bound_ctrl:1
	ds_read_u16_d16_hi v24, v157 offset:8448
	v_fma_f32 v58, v70, v46, v54
	v_and_b32_e32 v137, 0xffff0000, v92
	v_add_f32_dpp v49, v49, v49 row_ror:1 row_mask:0xf bank_mask:0xf bound_ctrl:1
	v_fma_f32 v59, v71, v47, v55
	v_add_f32_dpp v26, v26, v26 row_ror:1 row_mask:0xf bank_mask:0xf bound_ctrl:1
	v_lshlrev_b32_e32 v138, 16, v93
	s_nop 0
	v_fma_f32 v68, -v49, v32, v56
	v_fma_f32 v69, -v49, v33, v57
	v_fma_f32 v70, -v49, v34, v58
	v_fma_f32 v71, -v49, v35, v59
	v_cndmask_b32_e64 v60, v60, v26, s[12:13]
	v_and_b32_e32 v139, 0xffff0000, v93
	s_waitcnt lgkmcnt(0)
	v_mul_f32_e32 v25, v68, v4
	v_mul_f32_e32 v50, v68, v40
	v_fmac_f32_e32 v25, v69, v5
	v_fmac_f32_e32 v50, v69, v41
	v_fmac_f32_e32 v25, v70, v6
	v_fmac_f32_e32 v50, v70, v42
	v_fmac_f32_e32 v25, v71, v7
	v_fmac_f32_e32 v50, v71, v43
	v_mul_f32_e32 v52, v24, v12
	ds_read_b128 v[40:43], v156 offset:9904
	v_add_f32_dpp v25, v25, v25 row_ror:8 row_mask:0xf bank_mask:0xf bound_ctrl:1
	v_mul_f32_e32 v53, v24, v13
	v_add_f32_dpp v50, v50, v50 row_ror:8 row_mask:0xf bank_mask:0xf bound_ctrl:1
	ds_read_b128 v[28:31], v156 offset:9856
	v_mul_f32_e32 v54, v24, v14
	ds_read_b128 v[32:35], v156 offset:9872
	v_add_f32_dpp v25, v25, v25 row_ror:4 row_mask:0xf bank_mask:0xf bound_ctrl:1
	v_mul_f32_e32 v55, v24, v15
	v_add_f32_dpp v50, v50, v50 row_ror:4 row_mask:0xf bank_mask:0xf bound_ctrl:1
	ds_read_b128 v[36:39], v156 offset:9888
	v_fma_f32 v56, v68, v20, v52
	ds_read_b128 v[44:47], v156 offset:9920
	v_add_f32_dpp v25, v25, v25 row_ror:2 row_mask:0xf bank_mask:0xf bound_ctrl:1
	v_fma_f32 v57, v69, v21, v53
	v_add_f32_dpp v50, v50, v50 row_ror:2 row_mask:0xf bank_mask:0xf bound_ctrl:1
	ds_read_u16_d16_hi v48, v157 offset:9856
	v_fma_f32 v58, v70, v22, v54
	v_lshlrev_b32_e32 v140, 16, v94
	v_add_f32_dpp v25, v25, v25 row_ror:1 row_mask:0xf bank_mask:0xf bound_ctrl:1
	v_fma_f32 v59, v71, v23, v55
	v_add_f32_dpp v50, v50, v50 row_ror:1 row_mask:0xf bank_mask:0xf bound_ctrl:1
	v_and_b32_e32 v141, 0xffff0000, v94
	s_nop 0
	v_fma_f32 v68, -v25, v8, v56
	v_fma_f32 v69, -v25, v9, v57
	v_fma_f32 v70, -v25, v10, v58
	v_fma_f32 v71, -v25, v11, v59
	v_cndmask_b32_e64 v60, v60, v50, s[14:15]
	v_lshlrev_b32_e32 v142, 16, v95
	s_waitcnt lgkmcnt(0)
	v_mul_f32_e32 v49, v68, v28
	v_mul_f32_e32 v26, v68, v16
	v_fmac_f32_e32 v49, v69, v29
	v_fmac_f32_e32 v26, v69, v17
	v_fmac_f32_e32 v49, v70, v30
	v_fmac_f32_e32 v26, v70, v18
	v_fmac_f32_e32 v49, v71, v31
	v_fmac_f32_e32 v26, v71, v19
	v_mul_f32_e32 v52, v48, v36
	ds_read_b128 v[16:19], v156 offset:11312
	v_add_f32_dpp v49, v49, v49 row_ror:8 row_mask:0xf bank_mask:0xf bound_ctrl:1
	v_mul_f32_e32 v53, v48, v37
	v_add_f32_dpp v26, v26, v26 row_ror:8 row_mask:0xf bank_mask:0xf bound_ctrl:1
	ds_read_b128 v[4:7], v156 offset:11264
	v_mul_f32_e32 v54, v48, v38
	ds_read_b128 v[8:11], v156 offset:11280
	v_add_f32_dpp v49, v49, v49 row_ror:4 row_mask:0xf bank_mask:0xf bound_ctrl:1
	v_mul_f32_e32 v55, v48, v39
	v_add_f32_dpp v26, v26, v26 row_ror:4 row_mask:0xf bank_mask:0xf bound_ctrl:1
	ds_read_b128 v[12:15], v156 offset:11296
	v_fma_f32 v56, v68, v44, v52
	ds_read_b128 v[20:23], v156 offset:11328
	v_add_f32_dpp v49, v49, v49 row_ror:2 row_mask:0xf bank_mask:0xf bound_ctrl:1
	v_fma_f32 v57, v69, v45, v53
	v_add_f32_dpp v26, v26, v26 row_ror:2 row_mask:0xf bank_mask:0xf bound_ctrl:1
	ds_read_u16_d16_hi v24, v157 offset:11264
	v_fma_f32 v58, v70, v46, v54
	v_and_b32_e32 v143, 0xffff0000, v95
	v_add_f32_dpp v49, v49, v49 row_ror:1 row_mask:0xf bank_mask:0xf bound_ctrl:1
	v_fma_f32 v59, v71, v47, v55
	v_add_f32_dpp v26, v26, v26 row_ror:1 row_mask:0xf bank_mask:0xf bound_ctrl:1
	ds_write_b128 v155, v[136:139] offset:11264
	s_nop 0
	v_fma_f32 v68, -v49, v32, v56
	v_fma_f32 v69, -v49, v33, v57
	v_fma_f32 v70, -v49, v34, v58
	v_fma_f32 v71, -v49, v35, v59
	v_cndmask_b32_e64 v60, v60, v26, s[16:17]
	ds_write_b128 v155, v[140:143] offset:11344
	s_waitcnt lgkmcnt(0)
	v_mul_f32_e32 v25, v68, v4
	v_mul_f32_e32 v50, v68, v40
	v_fmac_f32_e32 v25, v69, v5
	v_fmac_f32_e32 v50, v69, v41
	v_fmac_f32_e32 v25, v70, v6
	v_fmac_f32_e32 v50, v70, v42
	v_fmac_f32_e32 v25, v71, v7
	v_fmac_f32_e32 v50, v71, v43
	v_mul_f32_e32 v52, v24, v12
	ds_read_b128 v[40:43], v156 offset:12720
	v_add_f32_dpp v25, v25, v25 row_ror:8 row_mask:0xf bank_mask:0xf bound_ctrl:1
	v_mul_f32_e32 v53, v24, v13
	v_add_f32_dpp v50, v50, v50 row_ror:8 row_mask:0xf bank_mask:0xf bound_ctrl:1
	ds_read_b128 v[28:31], v156 offset:12672
	v_mul_f32_e32 v54, v24, v14
	ds_read_b128 v[32:35], v156 offset:12688
	v_add_f32_dpp v25, v25, v25 row_ror:4 row_mask:0xf bank_mask:0xf bound_ctrl:1
	v_mul_f32_e32 v55, v24, v15
	v_add_f32_dpp v50, v50, v50 row_ror:4 row_mask:0xf bank_mask:0xf bound_ctrl:1
	ds_read_b128 v[36:39], v156 offset:12704
	v_fma_f32 v56, v68, v20, v52
	ds_read_b128 v[44:47], v156 offset:12736
	v_add_f32_dpp v25, v25, v25 row_ror:2 row_mask:0xf bank_mask:0xf bound_ctrl:1
	v_fma_f32 v57, v69, v21, v53
	v_add_f32_dpp v50, v50, v50 row_ror:2 row_mask:0xf bank_mask:0xf bound_ctrl:1
	ds_read_u16_d16_hi v48, v157 offset:12672
	v_fma_f32 v58, v70, v22, v54
	ds_write_b128 v165, v[96:99]
	v_add_f32_dpp v25, v25, v25 row_ror:1 row_mask:0xf bank_mask:0xf bound_ctrl:1
	v_fma_f32 v59, v71, v23, v55
	v_add_f32_dpp v50, v50, v50 row_ror:1 row_mask:0xf bank_mask:0xf bound_ctrl:1
	ds_write_b128 v166, v[100:103]
	s_nop 0
	v_fma_f32 v68, -v25, v8, v56
	v_fma_f32 v69, -v25, v9, v57
	v_fma_f32 v70, -v25, v10, v58
	v_fma_f32 v71, -v25, v11, v59
	v_cndmask_b32_e64 v60, v60, v50, s[18:19]
	global_load_dwordx4 v[88:91], v[144:145], off
	s_waitcnt lgkmcnt(0)
	v_mul_f32_e32 v49, v68, v28
	v_mul_f32_e32 v26, v68, v16
	v_fmac_f32_e32 v49, v69, v29
	v_fmac_f32_e32 v26, v69, v17
	v_fmac_f32_e32 v49, v70, v30
	v_fmac_f32_e32 v26, v70, v18
	v_fmac_f32_e32 v49, v71, v31
	v_fmac_f32_e32 v26, v71, v19
	v_mul_f32_e32 v52, v48, v36
	ds_read_b128 v[16:19], v156 offset:14128
	v_add_f32_dpp v49, v49, v49 row_ror:8 row_mask:0xf bank_mask:0xf bound_ctrl:1
	v_mul_f32_e32 v53, v48, v37
	v_add_f32_dpp v26, v26, v26 row_ror:8 row_mask:0xf bank_mask:0xf bound_ctrl:1
	ds_read_b128 v[4:7], v156 offset:14080
	v_mul_f32_e32 v54, v48, v38
	ds_read_b128 v[8:11], v156 offset:14096
	v_add_f32_dpp v49, v49, v49 row_ror:4 row_mask:0xf bank_mask:0xf bound_ctrl:1
	v_mul_f32_e32 v55, v48, v39
	v_add_f32_dpp v26, v26, v26 row_ror:4 row_mask:0xf bank_mask:0xf bound_ctrl:1
	ds_read_b128 v[12:15], v156 offset:14112
	v_fma_f32 v56, v68, v44, v52
	ds_read_b128 v[20:23], v156 offset:14144
	v_add_f32_dpp v49, v49, v49 row_ror:2 row_mask:0xf bank_mask:0xf bound_ctrl:1
	v_fma_f32 v57, v69, v45, v53
	v_add_f32_dpp v26, v26, v26 row_ror:2 row_mask:0xf bank_mask:0xf bound_ctrl:1
	ds_read_u16_d16_hi v24, v157 offset:14080
	v_fma_f32 v58, v70, v46, v54
	global_load_dwordx4 v[92:95], v[146:147], off
	v_add_f32_dpp v49, v49, v49 row_ror:1 row_mask:0xf bank_mask:0xf bound_ctrl:1
	v_fma_f32 v59, v71, v47, v55
	v_add_f32_dpp v26, v26, v26 row_ror:1 row_mask:0xf bank_mask:0xf bound_ctrl:1
	global_load_dwordx4 v[96:99], v[148:149], off
	s_nop 0
	v_fma_f32 v68, -v49, v32, v56
	v_fma_f32 v69, -v49, v33, v57
	v_fma_f32 v70, -v49, v34, v58
	v_fma_f32 v71, -v49, v35, v59
	v_cndmask_b32_e64 v60, v60, v26, s[20:21]
	global_load_dwordx4 v[100:103], v[150:151], off
	s_waitcnt lgkmcnt(0)
	v_mul_f32_e32 v25, v68, v4
	v_mul_f32_e32 v50, v68, v40
	v_fmac_f32_e32 v25, v69, v5
	v_fmac_f32_e32 v50, v69, v41
	v_fmac_f32_e32 v25, v70, v6
	v_fmac_f32_e32 v50, v70, v42
	v_fmac_f32_e32 v25, v71, v7
	v_fmac_f32_e32 v50, v71, v43
	v_mul_f32_e32 v52, v24, v12
	ds_read_b128 v[40:43], v156 offset:15536
	v_add_f32_dpp v25, v25, v25 row_ror:8 row_mask:0xf bank_mask:0xf bound_ctrl:1
	v_mul_f32_e32 v53, v24, v13
	v_add_f32_dpp v50, v50, v50 row_ror:8 row_mask:0xf bank_mask:0xf bound_ctrl:1
	ds_read_b128 v[28:31], v156 offset:15488
	v_mul_f32_e32 v54, v24, v14
	ds_read_b128 v[32:35], v156 offset:15504
	v_add_f32_dpp v25, v25, v25 row_ror:4 row_mask:0xf bank_mask:0xf bound_ctrl:1
	v_mul_f32_e32 v55, v24, v15
	v_add_f32_dpp v50, v50, v50 row_ror:4 row_mask:0xf bank_mask:0xf bound_ctrl:1
	ds_read_b128 v[36:39], v156 offset:15520
	v_fma_f32 v56, v68, v20, v52
	ds_read_b128 v[44:47], v156 offset:15552
	v_add_f32_dpp v25, v25, v25 row_ror:2 row_mask:0xf bank_mask:0xf bound_ctrl:1
	v_fma_f32 v57, v69, v21, v53
	v_add_f32_dpp v50, v50, v50 row_ror:2 row_mask:0xf bank_mask:0xf bound_ctrl:1
	ds_read_u16_d16_hi v48, v157 offset:15488
	v_fma_f32 v58, v70, v22, v54
	v_lshl_add_u64 v[144:145], v[144:145], 0, v[152:153]
	v_add_f32_dpp v25, v25, v25 row_ror:1 row_mask:0xf bank_mask:0xf bound_ctrl:1
	v_fma_f32 v59, v71, v23, v55
	v_add_f32_dpp v50, v50, v50 row_ror:1 row_mask:0xf bank_mask:0xf bound_ctrl:1
	v_lshl_add_u64 v[146:147], v[146:147], 0, v[152:153]
	s_nop 0
	v_fma_f32 v68, -v25, v8, v56
	v_fma_f32 v69, -v25, v9, v57
	v_fma_f32 v70, -v25, v10, v58
	v_fma_f32 v71, -v25, v11, v59
	v_cndmask_b32_e64 v60, v60, v50, s[22:23]
	v_lshl_add_u64 v[148:149], v[148:149], 0, v[62:63]
	s_waitcnt lgkmcnt(0)
	v_mul_f32_e32 v49, v68, v28
	v_mul_f32_e32 v26, v68, v16
	v_fmac_f32_e32 v49, v69, v29
	v_fmac_f32_e32 v26, v69, v17
	v_fmac_f32_e32 v49, v70, v30
	v_fmac_f32_e32 v26, v70, v18
	v_fmac_f32_e32 v49, v71, v31
	v_fmac_f32_e32 v26, v71, v19
	v_mul_f32_e32 v52, v48, v36
	ds_read_b128 v[16:19], v156 offset:16944
	v_add_f32_dpp v49, v49, v49 row_ror:8 row_mask:0xf bank_mask:0xf bound_ctrl:1
	v_mul_f32_e32 v53, v48, v37
	v_add_f32_dpp v26, v26, v26 row_ror:8 row_mask:0xf bank_mask:0xf bound_ctrl:1
	ds_read_b128 v[4:7], v156 offset:16896
	v_mul_f32_e32 v54, v48, v38
	ds_read_b128 v[8:11], v156 offset:16912
	v_add_f32_dpp v49, v49, v49 row_ror:4 row_mask:0xf bank_mask:0xf bound_ctrl:1
	v_mul_f32_e32 v55, v48, v39
	v_add_f32_dpp v26, v26, v26 row_ror:4 row_mask:0xf bank_mask:0xf bound_ctrl:1
	ds_read_b128 v[12:15], v156 offset:16928
	v_fma_f32 v56, v68, v44, v52
	ds_read_b128 v[20:23], v156 offset:16960
	v_add_f32_dpp v49, v49, v49 row_ror:2 row_mask:0xf bank_mask:0xf bound_ctrl:1
	v_fma_f32 v57, v69, v45, v53
	v_add_f32_dpp v26, v26, v26 row_ror:2 row_mask:0xf bank_mask:0xf bound_ctrl:1
	ds_read_u16_d16_hi v24, v157 offset:16896
	v_fma_f32 v58, v70, v46, v54
	v_lshl_add_u64 v[150:151], v[150:151], 0, v[64:65]
	v_add_f32_dpp v49, v49, v49 row_ror:1 row_mask:0xf bank_mask:0xf bound_ctrl:1
	v_fma_f32 v59, v71, v47, v55
	v_add_f32_dpp v26, v26, v26 row_ror:1 row_mask:0xf bank_mask:0xf bound_ctrl:1
	v_add_u32_e32 v158, s43, v162
	s_nop 0
	v_fma_f32 v68, -v49, v32, v56
	v_fma_f32 v69, -v49, v33, v57
	v_fma_f32 v70, -v49, v34, v58
	v_fma_f32 v71, -v49, v35, v59
	v_cndmask_b32_e64 v60, v60, v26, s[24:25]
	v_add_u32_e32 v159, s43, v163
	s_waitcnt lgkmcnt(0)
; DEVI void rw_chain_task(const Params& p, int l, int seq, int head, int quarter, char* smem) {
;     ...
;     for (int c = 0; c < nch; c += 4) {
;       lds_barrier();
;       RW_STORE(R1, B1);
;       RW_LOAD(R1, c + 5);
;       RW_COMPUTE(B0, c);
;       lds_barrier();
;       RW_STORE(R2, B0);
;       RW_LOAD(R2, c + 6);
;       RW_COMPUTE(B1, c + 1);
;       lds_barrier();
;       RW_STORE(R3, B1);
;       RW_LOAD(R3, c + 7);
;       RW_COMPUTE(B0, c + 2);
;       lds_barrier();
;       RW_STORE(R0, B0);
;       RW_LOAD(R0, c + 8);
;       RW_COMPUTE(B1, c + 3);
;     }
	v_mul_f32_e32 v25, v68, v4
	v_mul_f32_e32 v50, v68, v40
	v_fmac_f32_e32 v25, v69, v5
	v_fmac_f32_e32 v50, v69, v41
	v_fmac_f32_e32 v25, v70, v6
	v_fmac_f32_e32 v50, v70, v42
	v_fmac_f32_e32 v25, v71, v7
	v_fmac_f32_e32 v50, v71, v43
	v_mul_f32_e32 v52, v24, v12
	ds_read_b128 v[40:43], v156 offset:18352
	v_add_f32_dpp v25, v25, v25 row_ror:8 row_mask:0xf bank_mask:0xf bound_ctrl:1
	v_mul_f32_e32 v53, v24, v13
	v_add_f32_dpp v50, v50, v50 row_ror:8 row_mask:0xf bank_mask:0xf bound_ctrl:1
	ds_read_b128 v[28:31], v156 offset:18304
	v_mul_f32_e32 v54, v24, v14
	ds_read_b128 v[32:35], v156 offset:18320
	v_add_f32_dpp v25, v25, v25 row_ror:4 row_mask:0xf bank_mask:0xf bound_ctrl:1
	v_mul_f32_e32 v55, v24, v15
	v_add_f32_dpp v50, v50, v50 row_ror:4 row_mask:0xf bank_mask:0xf bound_ctrl:1
	ds_read_b128 v[36:39], v156 offset:18336
	v_fma_f32 v56, v68, v20, v52
	ds_read_b128 v[44:47], v156 offset:18368
	v_add_f32_dpp v25, v25, v25 row_ror:2 row_mask:0xf bank_mask:0xf bound_ctrl:1
	v_fma_f32 v57, v69, v21, v53
	v_add_f32_dpp v50, v50, v50 row_ror:2 row_mask:0xf bank_mask:0xf bound_ctrl:1
	ds_read_u16_d16_hi v48, v157 offset:18304
	v_fma_f32 v58, v70, v22, v54
	v_add_f32_dpp v25, v25, v25 row_ror:1 row_mask:0xf bank_mask:0xf bound_ctrl:1
	v_fma_f32 v59, v71, v23, v55
	v_add_f32_dpp v50, v50, v50 row_ror:1 row_mask:0xf bank_mask:0xf bound_ctrl:1
	s_nop 0
	v_fma_f32 v68, -v25, v8, v56
	v_fma_f32 v69, -v25, v9, v57
	v_fma_f32 v70, -v25, v10, v58
	v_fma_f32 v71, -v25, v11, v59
	v_cndmask_b32_e64 v60, v60, v50, s[26:27]
	s_waitcnt lgkmcnt(0)
	v_mul_f32_e32 v49, v68, v28
	v_mul_f32_e32 v26, v68, v16
	v_fmac_f32_e32 v49, v69, v29
	v_fmac_f32_e32 v26, v69, v17
	v_fmac_f32_e32 v49, v70, v30
	v_fmac_f32_e32 v26, v70, v18
	v_fmac_f32_e32 v49, v71, v31
	v_fmac_f32_e32 v26, v71, v19
	v_mul_f32_e32 v52, v48, v36
	ds_read_b128 v[16:19], v156 offset:19760
	v_add_f32_dpp v49, v49, v49 row_ror:8 row_mask:0xf bank_mask:0xf bound_ctrl:1
	v_mul_f32_e32 v53, v48, v37
	v_add_f32_dpp v26, v26, v26 row_ror:8 row_mask:0xf bank_mask:0xf bound_ctrl:1
	ds_read_b128 v[4:7], v156 offset:19712
	v_mul_f32_e32 v54, v48, v38
	ds_read_b128 v[8:11], v156 offset:19728
	v_add_f32_dpp v49, v49, v49 row_ror:4 row_mask:0xf bank_mask:0xf bound_ctrl:1
	v_mul_f32_e32 v55, v48, v39
	v_add_f32_dpp v26, v26, v26 row_ror:4 row_mask:0xf bank_mask:0xf bound_ctrl:1
	ds_read_b128 v[12:15], v156 offset:19744
	v_fma_f32 v56, v68, v44, v52
	ds_read_b128 v[20:23], v156 offset:19776
	v_add_f32_dpp v49, v49, v49 row_ror:2 row_mask:0xf bank_mask:0xf bound_ctrl:1
	v_fma_f32 v57, v69, v45, v53
	v_add_f32_dpp v26, v26, v26 row_ror:2 row_mask:0xf bank_mask:0xf bound_ctrl:1
	ds_read_u16_d16_hi v24, v157 offset:19712
	v_fma_f32 v58, v70, v46, v54
	v_add_f32_dpp v49, v49, v49 row_ror:1 row_mask:0xf bank_mask:0xf bound_ctrl:1
	v_fma_f32 v59, v71, v47, v55
	v_add_f32_dpp v26, v26, v26 row_ror:1 row_mask:0xf bank_mask:0xf bound_ctrl:1
	s_nop 0
	v_fma_f32 v68, -v49, v32, v56
	v_fma_f32 v69, -v49, v33, v57
	v_fma_f32 v70, -v49, v34, v58
	v_fma_f32 v71, -v49, v35, v59
	v_cndmask_b32_e64 v60, v60, v26, s[28:29]
	s_waitcnt lgkmcnt(0)
	v_mul_f32_e32 v25, v68, v4
	v_mul_f32_e32 v50, v68, v40
	v_fmac_f32_e32 v25, v69, v5
	v_fmac_f32_e32 v50, v69, v41
	v_fmac_f32_e32 v25, v70, v6
	v_fmac_f32_e32 v50, v70, v42
	v_fmac_f32_e32 v25, v71, v7
	v_fmac_f32_e32 v50, v71, v43
	v_mul_f32_e32 v52, v24, v12
	ds_read_b128 v[40:43], v156 offset:21168
	v_add_f32_dpp v25, v25, v25 row_ror:8 row_mask:0xf bank_mask:0xf bound_ctrl:1
	v_mul_f32_e32 v53, v24, v13
	v_add_f32_dpp v50, v50, v50 row_ror:8 row_mask:0xf bank_mask:0xf bound_ctrl:1
	ds_read_b128 v[28:31], v156 offset:21120
	v_mul_f32_e32 v54, v24, v14
	ds_read_b128 v[32:35], v156 offset:21136
	v_add_f32_dpp v25, v25, v25 row_ror:4 row_mask:0xf bank_mask:0xf bound_ctrl:1
	v_mul_f32_e32 v55, v24, v15
	v_add_f32_dpp v50, v50, v50 row_ror:4 row_mask:0xf bank_mask:0xf bound_ctrl:1
	ds_read_b128 v[36:39], v156 offset:21152
	v_fma_f32 v56, v68, v20, v52
	ds_read_b128 v[44:47], v156 offset:21184
	v_add_f32_dpp v25, v25, v25 row_ror:2 row_mask:0xf bank_mask:0xf bound_ctrl:1
	v_fma_f32 v57, v69, v21, v53
	v_add_f32_dpp v50, v50, v50 row_ror:2 row_mask:0xf bank_mask:0xf bound_ctrl:1
	ds_read_u16_d16_hi v48, v157 offset:21120
	v_fma_f32 v58, v70, v22, v54
	v_add_f32_dpp v25, v25, v25 row_ror:1 row_mask:0xf bank_mask:0xf bound_ctrl:1
	v_fma_f32 v59, v71, v23, v55
	v_add_f32_dpp v50, v50, v50 row_ror:1 row_mask:0xf bank_mask:0xf bound_ctrl:1
	s_nop 0
	v_fma_f32 v68, -v25, v8, v56
	v_fma_f32 v69, -v25, v9, v57
	v_fma_f32 v70, -v25, v10, v58
	v_fma_f32 v71, -v25, v11, v59
	v_cndmask_b32_e64 v60, v60, v50, s[30:31]
	s_waitcnt lgkmcnt(0)
	v_mul_f32_e32 v49, v68, v28
	v_mul_f32_e32 v26, v68, v16
	v_fmac_f32_e32 v49, v69, v29
	v_fmac_f32_e32 v26, v69, v17
	v_fmac_f32_e32 v49, v70, v30
	v_fmac_f32_e32 v26, v70, v18
	v_fmac_f32_e32 v49, v71, v31
	v_fmac_f32_e32 v26, v71, v19
	v_mul_f32_e32 v52, v48, v36
	ds_read_b128 v[16:19], v158 offset:48
	v_add_f32_dpp v49, v49, v49 row_ror:8 row_mask:0xf bank_mask:0xf bound_ctrl:1
	v_mul_f32_e32 v53, v48, v37
	v_add_f32_dpp v26, v26, v26 row_ror:8 row_mask:0xf bank_mask:0xf bound_ctrl:1
	ds_read_b128 v[4:7], v158 offset:0
	v_mul_f32_e32 v54, v48, v38
	ds_read_b128 v[8:11], v158 offset:16
	v_add_f32_dpp v49, v49, v49 row_ror:4 row_mask:0xf bank_mask:0xf bound_ctrl:1
	v_mul_f32_e32 v55, v48, v39
	v_add_f32_dpp v26, v26, v26 row_ror:4 row_mask:0xf bank_mask:0xf bound_ctrl:1
	ds_read_b128 v[12:15], v158 offset:32
	v_fma_f32 v56, v68, v44, v52
	ds_read_b128 v[20:23], v158 offset:64
	v_add_f32_dpp v49, v49, v49 row_ror:2 row_mask:0xf bank_mask:0xf bound_ctrl:1
	v_fma_f32 v57, v69, v45, v53
	v_add_f32_dpp v26, v26, v26 row_ror:2 row_mask:0xf bank_mask:0xf bound_ctrl:1
	ds_read_u16_d16_hi v24, v159 offset:0
	v_fma_f32 v58, v70, v46, v54
	v_add_f32_dpp v49, v49, v49 row_ror:1 row_mask:0xf bank_mask:0xf bound_ctrl:1
	v_fma_f32 v59, v71, v47, v55
	v_add_f32_dpp v26, v26, v26 row_ror:1 row_mask:0xf bank_mask:0xf bound_ctrl:1
	s_nop 0
	v_fma_f32 v68, -v49, v32, v56
	v_fma_f32 v69, -v49, v33, v57
	v_fma_f32 v70, -v49, v34, v58
	v_fma_f32 v71, -v49, v35, v59
	v_cndmask_b32_e64 v60, v60, v26, s[34:35]
	s_add_u32 s41, s41, 4
	s_cmpk_lt_u32 s41, 0x400
	s_cbranch_scc1 .Lrwc_loop
; DEVI void rw_chain_task(const Params& p, int l, int seq, int head, int quarter, char* smem) {
;     ...
;   float* so = seq < 2 ? p.out + O_PRWS + ((((size_t)l * 2 + seq) * 12 + head) * 64 + i) * 64 + jl * 4
;                       : p.out + O_SRWS + ((((size_t)l * 8 + (seq - 2)) * 12 + head) * 64 + i) * 64 + jl * 4;
;   *(float4*)so = make_float4(S[0], S[1], S[2], S[3]);
	s_waitcnt lgkmcnt(0)
	v_mul_f32_e32 v50, v68, v40
	v_fmac_f32_e32 v50, v69, v41
	v_fmac_f32_e32 v50, v70, v42
	v_fmac_f32_e32 v50, v71, v43
	s_nop 1
	v_add_f32_dpp v50, v50, v50 row_ror:8 row_mask:0xf bank_mask:0xf bound_ctrl:1
	s_nop 1
	v_add_f32_dpp v50, v50, v50 row_ror:4 row_mask:0xf bank_mask:0xf bound_ctrl:1
	s_nop 1
	v_add_f32_dpp v50, v50, v50 row_ror:2 row_mask:0xf bank_mask:0xf bound_ctrl:1
	s_nop 1
	v_add_f32_dpp v50, v50, v50 row_ror:1 row_mask:0xf bank_mask:0xf bound_ctrl:1
	s_nop 0
	v_cndmask_b32_e64 v60, v60, v50, s[36:37]
	v_bfe_u32 v61, v60, 16, 1
	v_add3_u32 v61, v60, v61, s33
	global_store_short_d16_hi v[160:161], v61, off
	s_waitcnt vmcnt(0)
	s_movk_i32 s41, 0x3fc
	s_mov_b32 s42, 0xffff0000
	s_mov_b32 s43, 0xfffd0000
	s_mov_b32 s45, 0xfffe0000
	s_mov_b64 s[46:47], 0x40000
	v_readlane_b32 s38, v253, 39
	v_readlane_b32 s39, v253, 40
	v_and_b32_e32 v136, 16, v1
	v_cmp_eq_u32_e32 vcc, 0, v136
	v_readlane_b32 s4, v254, 2
	s_lshl_b32 s4, s4, 1
	v_readlane_b32 s6, v253, 37
	v_readlane_b32 s5, v254, 3
	v_readlane_b32 s7, v253, 38
	s_add_u32 s4, s4, s6
	s_addc_u32 s5, 0, s7
	s_mul_i32 s5, s5, 12
	s_mul_hi_u32 s6, s4, 12
	s_add_i32 s6, s6, s5
	s_mul_i32 s4, s4, 12
	v_readlane_b32 s5, v253, 4
	s_add_u32 s4, s4, s5
	v_readlane_b32 s5, v253, 5
	s_addc_u32 s5, s6, s5
	s_lshl_b64 s[4:5], s[4:5], 14
	v_readlane_b32 s6, v253, 2
	v_ashrrev_i32_e32 v155, 31, v154
	s_add_u32 s4, s6, s4
	v_readlane_b32 s6, v253, 3
	s_addc_u32 s5, s6, s5
	s_waitcnt vmcnt(19)
	v_lshlrev_b64 v[4:5], 8, v[154:155]
	v_lshl_add_u64 v[4:5], s[4:5], 0, v[4:5]
	v_lshlrev_b32_e32 v6, 4, v3
	v_mov_b32_e32 v7, v2
	v_lshl_add_u64 v[4:5], v[4:5], 0, v[6:7]
	s_barrier
	global_store_dwordx4 v[4:5], v[68:71], off
	s_and_b64 vcc, exec, s[2:3]
	s_cbranch_vccnz .LBB0_1001
